# FFN-down K-loops: same A(0,0) DMA-group move as FFN-up; attention: redundant tile-end barriers removed (one barrier per KV tile), loop-exit barrier added
# speedup vs baseline: 1.0163x; 1.0037x over previous
.LBB0_571:
	v_cndmask_b32_e64 v249, v220, v249, s[6:7]
	v_mul_f32_e32 v194, 0xbe0293ee, v249
	v_fmamk_f32 v146, v146, 0x3e0293ee, v194
	v_fmamk_f32 v147, v147, 0x3e0293ee, v194
	v_fmamk_f32 v148, v148, 0x3e0293ee, v194
	v_fmamk_f32 v149, v149, 0x3e0293ee, v194
	v_fmamk_f32 v150, v150, 0x3e0293ee, v194
	v_fmamk_f32 v151, v151, 0x3e0293ee, v194
	v_fmamk_f32 v152, v152, 0x3e0293ee, v194
	v_fmamk_f32 v153, v153, 0x3e0293ee, v194
	v_fmamk_f32 v154, v154, 0x3e0293ee, v194
	v_fmamk_f32 v155, v155, 0x3e0293ee, v194
	v_fmamk_f32 v156, v156, 0x3e0293ee, v194
	v_fmamk_f32 v157, v157, 0x3e0293ee, v194
	v_fmamk_f32 v158, v158, 0x3e0293ee, v194
	v_fmamk_f32 v159, v159, 0x3e0293ee, v194
	v_fmamk_f32 v160, v160, 0x3e0293ee, v194
	v_fmamk_f32 v161, v161, 0x3e0293ee, v194
	v_fmamk_f32 v130, v130, 0x3e0293ee, v194
	v_fmamk_f32 v131, v131, 0x3e0293ee, v194
	v_fmamk_f32 v132, v132, 0x3e0293ee, v194
	v_fmamk_f32 v133, v133, 0x3e0293ee, v194
	v_fmamk_f32 v134, v134, 0x3e0293ee, v194
	v_fmamk_f32 v135, v135, 0x3e0293ee, v194
	v_fmamk_f32 v136, v136, 0x3e0293ee, v194
	v_fmamk_f32 v137, v137, 0x3e0293ee, v194
	v_fmamk_f32 v138, v138, 0x3e0293ee, v194
	v_fmamk_f32 v139, v139, 0x3e0293ee, v194
	v_fmamk_f32 v140, v140, 0x3e0293ee, v194
	v_fmamk_f32 v141, v141, 0x3e0293ee, v194
	v_fmamk_f32 v142, v142, 0x3e0293ee, v194
	v_fmamk_f32 v143, v143, 0x3e0293ee, v194
	v_fmamk_f32 v144, v144, 0x3e0293ee, v194
	v_fmac_f32_e32 v194, 0x3e0293ee, v145
	v_exp_f32_e32 v145, v146
	v_exp_f32_e32 v146, v147
	v_exp_f32_e32 v147, v148
	v_exp_f32_e32 v148, v149
	v_exp_f32_e32 v149, v150
	v_exp_f32_e32 v150, v151
	v_exp_f32_e32 v151, v152
	v_exp_f32_e32 v152, v153
	v_exp_f32_e32 v153, v154
	v_exp_f32_e32 v154, v155
	v_exp_f32_e32 v155, v156
	v_exp_f32_e32 v156, v157
	v_exp_f32_e32 v157, v158
	v_exp_f32_e32 v158, v159
	v_exp_f32_e32 v159, v160
	v_exp_f32_e32 v160, v161
	v_exp_f32_e32 v161, v130
	v_add_f32_e32 v130, 0, v145
	v_add_f32_e32 v130, v146, v130
	v_add_f32_e32 v130, v147, v130
	v_add_f32_e32 v130, v148, v130
	v_add_f32_e32 v130, v149, v130
	v_add_f32_e32 v130, v150, v130
	v_add_f32_e32 v130, v151, v130
	v_add_f32_e32 v130, v152, v130
	v_add_f32_e32 v130, v153, v130
	v_add_f32_e32 v130, v154, v130
	v_add_f32_e32 v130, v155, v130
	v_add_f32_e32 v130, v156, v130
	v_add_f32_e32 v130, v157, v130
	v_exp_f32_e32 v195, v131
	v_add_f32_e32 v130, v158, v130
	v_exp_f32_e32 v196, v132
	v_add_f32_e32 v130, v159, v130
	v_exp_f32_e32 v197, v133
	v_add_f32_e32 v130, v160, v130
	v_exp_f32_e32 v198, v134
	v_add_f32_e32 v130, v161, v130
	v_exp_f32_e32 v199, v135
	v_add_f32_e32 v130, v195, v130
	v_exp_f32_e32 v200, v136
	v_add_f32_e32 v130, v196, v130
	v_exp_f32_e32 v201, v137
	v_add_f32_e32 v130, v197, v130
	v_exp_f32_e32 v202, v138
	v_add_f32_e32 v130, v198, v130
	v_exp_f32_e32 v203, v139
	v_add_f32_e32 v130, v199, v130
	v_exp_f32_e32 v204, v140
	v_add_f32_e32 v130, v200, v130
	v_exp_f32_e32 v205, v141
	v_add_f32_e32 v130, v201, v130
	v_exp_f32_e32 v206, v142
	v_add_f32_e32 v130, v202, v130
	v_exp_f32_e32 v207, v143
	v_add_f32_e32 v130, v203, v130
	v_exp_f32_e32 v208, v144
	v_add_f32_e32 v130, v204, v130
	v_exp_f32_e32 v194, v194
	v_add_f32_e32 v130, v205, v130
	v_add_f32_e32 v130, v206, v130
	v_add_f32_e32 v130, v207, v130
	v_add_f32_e32 v130, v208, v130
	v_add_f32_e32 v247, v194, v130
	v_mov_b32_e32 v248, v247
	s_nop 1
	v_permlane32_swap_b32_e32 v247, v248
	v_cvt_pk_bf16_f32 v130, v145, v146
	v_cvt_pk_bf16_f32 v131, v147, v148
	v_cvt_pk_bf16_f32 v132, v149, v150
	v_cvt_pk_bf16_f32 v133, v151, v152
	v_cvt_pk_bf16_f32 v134, v153, v154
	v_cvt_pk_bf16_f32 v135, v155, v156
	v_cvt_pk_bf16_f32 v136, v157, v158
	v_cvt_pk_bf16_f32 v137, v159, v160
	v_cvt_pk_bf16_f32 v138, v161, v195
	v_cvt_pk_bf16_f32 v139, v196, v197
	v_cvt_pk_bf16_f32 v140, v198, v199
	v_cvt_pk_bf16_f32 v141, v200, v201
	v_cvt_pk_bf16_f32 v142, v202, v203
	v_cvt_pk_bf16_f32 v143, v204, v205
	v_cvt_pk_bf16_f32 v144, v206, v207
	v_cvt_pk_bf16_f32 v145, v208, v194
	s_nop 0
	v_permlane32_swap_b32_e32 v130, v132
	v_permlane32_swap_b32_e32 v131, v133
	v_permlane32_swap_b32_e32 v134, v136
	v_permlane32_swap_b32_e32 v135, v137
	v_permlane32_swap_b32_e32 v138, v140
	v_permlane32_swap_b32_e32 v139, v141
	v_permlane32_swap_b32_e32 v142, v144
	v_permlane32_swap_b32_e32 v143, v145
	ds_read_b64_tr_b16 v[146:147], v224 offset:0
	ds_read_b64_tr_b16 v[148:149], v224 offset:0x800
	ds_read_b64_tr_b16 v[150:151], v224 offset:0x1000
	ds_read_b64_tr_b16 v[152:153], v224 offset:0x1800
	ds_read_b64_tr_b16 v[154:155], v224 offset:0x2000
	ds_read_b64_tr_b16 v[156:157], v224 offset:0x2800
	ds_read_b64_tr_b16 v[158:159], v224 offset:0x3000
	ds_read_b64_tr_b16 v[160:161], v224 offset:0x3800
	s_nop 0
	s_waitcnt lgkmcnt(6)
	v_mfma_f32_32x32x16_bf16 v[2:17], v[130:133], v[146:149], v[2:17]
	ds_read_b64_tr_b16 v[146:147], v224 offset:0x200
	ds_read_b64_tr_b16 v[148:149], v224 offset:0xa00
	s_waitcnt lgkmcnt(6)
	v_mfma_f32_32x32x16_bf16 v[2:17], v[134:137], v[150:153], v[2:17]
	ds_read_b64_tr_b16 v[150:151], v224 offset:0x1200
	ds_read_b64_tr_b16 v[152:153], v224 offset:0x1a00
	s_waitcnt lgkmcnt(6)
	v_mfma_f32_32x32x16_bf16 v[2:17], v[138:141], v[154:157], v[2:17]
	ds_read_b64_tr_b16 v[154:155], v224 offset:0x2200
	ds_read_b64_tr_b16 v[156:157], v224 offset:0x2a00
	s_waitcnt lgkmcnt(6)
	v_mfma_f32_32x32x16_bf16 v[2:17], v[142:145], v[158:161], v[2:17]
	ds_read_b64_tr_b16 v[158:159], v224 offset:0x3200
	ds_read_b64_tr_b16 v[160:161], v224 offset:0x3a00
	s_waitcnt lgkmcnt(6)
	v_mfma_f32_32x32x16_bf16 v[114:129], v[130:133], v[146:149], v[114:129]
	ds_read_b64_tr_b16 v[146:147], v224 offset:0x400
	ds_read_b64_tr_b16 v[148:149], v224 offset:0xc00
	s_waitcnt lgkmcnt(6)
	v_mfma_f32_32x32x16_bf16 v[114:129], v[134:137], v[150:153], v[114:129]
	ds_read_b64_tr_b16 v[150:151], v224 offset:0x1400
	ds_read_b64_tr_b16 v[152:153], v224 offset:0x1c00
	s_waitcnt lgkmcnt(6)
	v_mfma_f32_32x32x16_bf16 v[114:129], v[138:141], v[154:157], v[114:129]
	ds_read_b64_tr_b16 v[154:155], v224 offset:0x2400
	ds_read_b64_tr_b16 v[156:157], v224 offset:0x2c00
	s_waitcnt lgkmcnt(6)
	v_mfma_f32_32x32x16_bf16 v[114:129], v[142:145], v[158:161], v[114:129]
	ds_read_b64_tr_b16 v[158:159], v224 offset:0x3400
	ds_read_b64_tr_b16 v[160:161], v224 offset:0x3c00
	s_waitcnt lgkmcnt(6)
	v_mfma_f32_32x32x16_bf16 v[98:113], v[130:133], v[146:149], v[98:113]
	ds_read_b64_tr_b16 v[146:147], v224 offset:0x600
	ds_read_b64_tr_b16 v[148:149], v224 offset:0xe00
	s_waitcnt lgkmcnt(6)
	v_mfma_f32_32x32x16_bf16 v[98:113], v[134:137], v[150:153], v[98:113]
	ds_read_b64_tr_b16 v[150:151], v224 offset:0x1600
	ds_read_b64_tr_b16 v[152:153], v224 offset:0x1e00
	s_waitcnt lgkmcnt(6)
	v_mfma_f32_32x32x16_bf16 v[98:113], v[138:141], v[154:157], v[98:113]
	ds_read_b64_tr_b16 v[154:155], v224 offset:0x2600
	ds_read_b64_tr_b16 v[156:157], v224 offset:0x2e00
	s_waitcnt lgkmcnt(6)
	v_mfma_f32_32x32x16_bf16 v[98:113], v[142:145], v[158:161], v[98:113]
	ds_read_b64_tr_b16 v[158:159], v224 offset:0x3600
	ds_read_b64_tr_b16 v[160:161], v224 offset:0x3e00
	s_waitcnt lgkmcnt(6)
	v_mfma_f32_32x32x16_bf16 v[82:97], v[130:133], v[146:149], v[82:97]
	ds_read_b64_tr_b16 v[146:147], v234 offset:0
	ds_read_b64_tr_b16 v[148:149], v234 offset:0x800
	s_waitcnt lgkmcnt(6)
	v_mfma_f32_32x32x16_bf16 v[82:97], v[134:137], v[150:153], v[82:97]
	ds_read_b64_tr_b16 v[150:151], v234 offset:0x1000
	ds_read_b64_tr_b16 v[152:153], v234 offset:0x1800
	s_waitcnt lgkmcnt(6)
	v_mfma_f32_32x32x16_bf16 v[82:97], v[138:141], v[154:157], v[82:97]
	ds_read_b64_tr_b16 v[154:155], v234 offset:0x2000
	ds_read_b64_tr_b16 v[156:157], v234 offset:0x2800
	s_waitcnt lgkmcnt(6)
	v_mfma_f32_32x32x16_bf16 v[82:97], v[142:145], v[158:161], v[82:97]
	ds_read_b64_tr_b16 v[158:159], v234 offset:0x3000
	ds_read_b64_tr_b16 v[160:161], v234 offset:0x3800
	s_waitcnt lgkmcnt(6)
	v_mfma_f32_32x32x16_bf16 v[66:81], v[130:133], v[146:149], v[66:81]
	ds_read_b64_tr_b16 v[146:147], v234 offset:0x200
	ds_read_b64_tr_b16 v[148:149], v234 offset:0xa00
	s_waitcnt lgkmcnt(6)
	v_mfma_f32_32x32x16_bf16 v[66:81], v[134:137], v[150:153], v[66:81]
	ds_read_b64_tr_b16 v[150:151], v234 offset:0x1200
	ds_read_b64_tr_b16 v[152:153], v234 offset:0x1a00
	s_waitcnt lgkmcnt(6)
	v_mfma_f32_32x32x16_bf16 v[66:81], v[138:141], v[154:157], v[66:81]
	ds_read_b64_tr_b16 v[154:155], v234 offset:0x2200
	ds_read_b64_tr_b16 v[156:157], v234 offset:0x2a00
	s_waitcnt lgkmcnt(6)
	v_mfma_f32_32x32x16_bf16 v[66:81], v[142:145], v[158:161], v[66:81]
	ds_read_b64_tr_b16 v[158:159], v234 offset:0x3200
	ds_read_b64_tr_b16 v[160:161], v234 offset:0x3a00
	s_waitcnt lgkmcnt(6)
	v_mfma_f32_32x32x16_bf16 v[50:65], v[130:133], v[146:149], v[50:65]
	ds_read_b64_tr_b16 v[146:147], v234 offset:0x400
	ds_read_b64_tr_b16 v[148:149], v234 offset:0xc00
	s_waitcnt lgkmcnt(6)
	v_mfma_f32_32x32x16_bf16 v[50:65], v[134:137], v[150:153], v[50:65]
	ds_read_b64_tr_b16 v[150:151], v234 offset:0x1400
	ds_read_b64_tr_b16 v[152:153], v234 offset:0x1c00
	s_waitcnt lgkmcnt(6)
	v_mfma_f32_32x32x16_bf16 v[50:65], v[138:141], v[154:157], v[50:65]
	ds_read_b64_tr_b16 v[154:155], v234 offset:0x2400
	ds_read_b64_tr_b16 v[156:157], v234 offset:0x2c00
	s_waitcnt lgkmcnt(6)
	v_mfma_f32_32x32x16_bf16 v[50:65], v[142:145], v[158:161], v[50:65]
	ds_read_b64_tr_b16 v[158:159], v234 offset:0x3400
	ds_read_b64_tr_b16 v[160:161], v234 offset:0x3c00
	s_waitcnt lgkmcnt(6)
	v_mfma_f32_32x32x16_bf16 v[34:49], v[130:133], v[146:149], v[34:49]
	ds_read_b64_tr_b16 v[146:147], v234 offset:0x600
	ds_read_b64_tr_b16 v[148:149], v234 offset:0xe00
	s_waitcnt lgkmcnt(6)
	v_mfma_f32_32x32x16_bf16 v[34:49], v[134:137], v[150:153], v[34:49]
	ds_read_b64_tr_b16 v[150:151], v234 offset:0x1600
	ds_read_b64_tr_b16 v[152:153], v234 offset:0x1e00
	s_waitcnt lgkmcnt(6)
	v_mfma_f32_32x32x16_bf16 v[34:49], v[138:141], v[154:157], v[34:49]
	ds_read_b64_tr_b16 v[154:155], v234 offset:0x2600
	ds_read_b64_tr_b16 v[156:157], v234 offset:0x2e00
	s_waitcnt lgkmcnt(6)
	v_mfma_f32_32x32x16_bf16 v[34:49], v[142:145], v[158:161], v[34:49]
	ds_read_b64_tr_b16 v[158:159], v234 offset:0x3600
	ds_read_b64_tr_b16 v[160:161], v234 offset:0x3e00
	s_waitcnt lgkmcnt(6)
	v_mfma_f32_32x32x16_bf16 v[18:33], v[130:133], v[146:149], v[18:33]
	s_waitcnt lgkmcnt(4)
	v_mfma_f32_32x32x16_bf16 v[18:33], v[134:137], v[150:153], v[18:33]
	s_waitcnt lgkmcnt(2)
	v_mfma_f32_32x32x16_bf16 v[18:33], v[138:141], v[154:157], v[18:33]
	s_waitcnt lgkmcnt(0)
	v_mfma_f32_32x32x16_bf16 v[18:33], v[142:145], v[158:161], v[18:33]
	s_add_i32 s14, s97, -1
	v_lshl_add_u64 v[222:223], v[216:217], 0, s[44:45]
	v_lshl_add_u64 v[220:221], v[218:219], 0, s[44:45]
	s_mov_b64 s[70:71], 0xa0000
	s_waitcnt vmcnt(0)

.LBB0_579:
	v_cndmask_b32_e64 v249, v251, v249, s[6:7]
	v_mul_f32_e32 v194, 0xbe0293ee, v249
	v_fmamk_f32 v146, v146, 0x3e0293ee, v194
	v_fmamk_f32 v147, v147, 0x3e0293ee, v194
	v_fmamk_f32 v148, v148, 0x3e0293ee, v194
	v_fmamk_f32 v149, v149, 0x3e0293ee, v194
	v_fmamk_f32 v150, v150, 0x3e0293ee, v194
	v_fmamk_f32 v151, v151, 0x3e0293ee, v194
	v_fmamk_f32 v152, v152, 0x3e0293ee, v194
	v_fmamk_f32 v153, v153, 0x3e0293ee, v194
	v_fmamk_f32 v154, v154, 0x3e0293ee, v194
	v_fmamk_f32 v155, v155, 0x3e0293ee, v194
	v_fmamk_f32 v156, v156, 0x3e0293ee, v194
	v_fmamk_f32 v157, v157, 0x3e0293ee, v194
	v_fmamk_f32 v158, v158, 0x3e0293ee, v194
	v_fmamk_f32 v159, v159, 0x3e0293ee, v194
	v_fmamk_f32 v160, v160, 0x3e0293ee, v194
	v_fmamk_f32 v161, v161, 0x3e0293ee, v194
	v_fmamk_f32 v130, v130, 0x3e0293ee, v194
	v_fmamk_f32 v131, v131, 0x3e0293ee, v194
	v_fmamk_f32 v132, v132, 0x3e0293ee, v194
	v_fmamk_f32 v133, v133, 0x3e0293ee, v194
	v_fmamk_f32 v134, v134, 0x3e0293ee, v194
	v_fmamk_f32 v135, v135, 0x3e0293ee, v194
	v_fmamk_f32 v136, v136, 0x3e0293ee, v194
	v_fmamk_f32 v137, v137, 0x3e0293ee, v194
	v_fmamk_f32 v138, v138, 0x3e0293ee, v194
	v_fmamk_f32 v139, v139, 0x3e0293ee, v194
	v_fmamk_f32 v140, v140, 0x3e0293ee, v194
	v_fmamk_f32 v141, v141, 0x3e0293ee, v194
	v_fmamk_f32 v142, v142, 0x3e0293ee, v194
	v_fmamk_f32 v143, v143, 0x3e0293ee, v194
	v_fmamk_f32 v144, v144, 0x3e0293ee, v194
	v_fmac_f32_e32 v194, 0x3e0293ee, v145
	v_exp_f32_e32 v145, v146
	v_exp_f32_e32 v195, v147
	v_exp_f32_e32 v148, v148
	v_exp_f32_e32 v149, v149
	v_exp_f32_e32 v150, v150
	v_exp_f32_e32 v196, v130
	v_add_f32_e32 v130, 0, v145
	v_exp_f32_e32 v151, v151
	v_add_f32_e32 v130, v195, v130
	v_exp_f32_e32 v152, v152
	v_add_f32_e32 v130, v148, v130
	v_exp_f32_e32 v153, v153
	v_add_f32_e32 v130, v149, v130
	v_exp_f32_e32 v154, v154
	v_add_f32_e32 v130, v150, v130
	v_exp_f32_e32 v155, v155
	v_add_f32_e32 v130, v151, v130
	v_exp_f32_e32 v156, v156
	v_add_f32_e32 v130, v152, v130
	v_exp_f32_e32 v157, v157
	v_add_f32_e32 v130, v153, v130
	v_exp_f32_e32 v158, v158
	v_add_f32_e32 v130, v154, v130
	v_exp_f32_e32 v159, v159
	v_add_f32_e32 v130, v155, v130
	v_exp_f32_e32 v160, v160
	v_add_f32_e32 v130, v156, v130
	v_exp_f32_e32 v161, v161
	v_add_f32_e32 v130, v157, v130
	v_add_f32_e32 v130, v158, v130
	v_exp_f32_e32 v197, v131
	v_add_f32_e32 v130, v159, v130
	v_exp_f32_e32 v198, v132
	v_add_f32_e32 v130, v160, v130
	v_exp_f32_e32 v199, v133
	v_add_f32_e32 v130, v161, v130
	v_exp_f32_e32 v200, v134
	v_add_f32_e32 v130, v196, v130
	v_exp_f32_e32 v201, v135
	v_add_f32_e32 v130, v197, v130
	v_exp_f32_e32 v202, v136
	v_add_f32_e32 v130, v198, v130
	v_exp_f32_e32 v203, v137
	v_add_f32_e32 v130, v199, v130
	v_exp_f32_e32 v204, v138
	v_add_f32_e32 v130, v200, v130
	v_exp_f32_e32 v205, v139
	v_add_f32_e32 v130, v201, v130
	v_exp_f32_e32 v206, v140
	v_add_f32_e32 v130, v202, v130
	v_exp_f32_e32 v207, v141
	v_add_f32_e32 v130, v203, v130
	v_exp_f32_e32 v208, v142
	v_add_f32_e32 v130, v204, v130
	v_exp_f32_e32 v209, v143
	v_add_f32_e32 v130, v205, v130
	v_exp_f32_e32 v251, v144
	v_add_f32_e32 v130, v206, v130
	v_exp_f32_e32 v194, v194
	v_add_f32_e32 v130, v207, v130
	v_add_f32_e32 v130, v208, v130
	v_add_f32_e32 v130, v209, v130
	v_add_f32_e32 v130, v251, v130
	v_add_f32_e32 v146, v194, v130
	v_mov_b32_e32 v147, v146
	s_nop 1
	v_permlane32_swap_b32_e32 v146, v147
	v_cvt_pk_bf16_f32 v130, v145, v195
	v_cvt_pk_bf16_f32 v131, v148, v149
	v_cvt_pk_bf16_f32 v132, v150, v151
	v_cvt_pk_bf16_f32 v133, v152, v153
	v_cvt_pk_bf16_f32 v134, v154, v155
	v_cvt_pk_bf16_f32 v135, v156, v157
	v_cvt_pk_bf16_f32 v136, v158, v159
	v_cvt_pk_bf16_f32 v137, v160, v161
	v_cvt_pk_bf16_f32 v138, v196, v197
	v_cvt_pk_bf16_f32 v139, v198, v199
	v_cvt_pk_bf16_f32 v140, v200, v201
	v_cvt_pk_bf16_f32 v141, v202, v203
	v_cvt_pk_bf16_f32 v142, v204, v205
	v_cvt_pk_bf16_f32 v143, v206, v207
	v_cvt_pk_bf16_f32 v144, v208, v209
	v_cvt_pk_bf16_f32 v145, v251, v194
	s_nop 0
	v_permlane32_swap_b32_e32 v130, v132
	v_permlane32_swap_b32_e32 v131, v133
	v_permlane32_swap_b32_e32 v134, v136
	v_permlane32_swap_b32_e32 v135, v137
	v_permlane32_swap_b32_e32 v138, v140
	v_permlane32_swap_b32_e32 v139, v141
	v_permlane32_swap_b32_e32 v142, v144
	v_permlane32_swap_b32_e32 v143, v145
	ds_read_b64_tr_b16 v[148:149], v235 offset:0
	ds_read_b64_tr_b16 v[150:151], v235 offset:0x800
	ds_read_b64_tr_b16 v[152:153], v235 offset:0x1000
	ds_read_b64_tr_b16 v[154:155], v235 offset:0x1800
	ds_read_b64_tr_b16 v[156:157], v235 offset:0x2000
	ds_read_b64_tr_b16 v[158:159], v235 offset:0x2800
	ds_read_b64_tr_b16 v[194:195], v235 offset:0x3000
	ds_read_b64_tr_b16 v[196:197], v235 offset:0x3800
	s_nop 0
	s_waitcnt lgkmcnt(6)
	v_mfma_f32_32x32x16_bf16 v[2:17], v[130:133], v[148:151], v[2:17]
	ds_read_b64_tr_b16 v[148:149], v235 offset:0x200
	ds_read_b64_tr_b16 v[150:151], v235 offset:0xa00
	s_waitcnt lgkmcnt(6)
	v_mfma_f32_32x32x16_bf16 v[2:17], v[134:137], v[152:155], v[2:17]
	ds_read_b64_tr_b16 v[152:153], v235 offset:0x1200
	ds_read_b64_tr_b16 v[154:155], v235 offset:0x1a00
	s_waitcnt lgkmcnt(6)
	v_mfma_f32_32x32x16_bf16 v[2:17], v[138:141], v[156:159], v[2:17]
	ds_read_b64_tr_b16 v[156:157], v235 offset:0x2200
	ds_read_b64_tr_b16 v[158:159], v235 offset:0x2a00
	s_waitcnt lgkmcnt(6)
	v_mfma_f32_32x32x16_bf16 v[2:17], v[142:145], v[194:197], v[2:17]
	ds_read_b64_tr_b16 v[194:195], v235 offset:0x3200
	ds_read_b64_tr_b16 v[196:197], v235 offset:0x3a00
	s_waitcnt lgkmcnt(6)
	v_mfma_f32_32x32x16_bf16 v[114:129], v[130:133], v[148:151], v[114:129]
	ds_read_b64_tr_b16 v[148:149], v235 offset:0x400
	ds_read_b64_tr_b16 v[150:151], v235 offset:0xc00
	s_waitcnt lgkmcnt(6)
	v_mfma_f32_32x32x16_bf16 v[114:129], v[134:137], v[152:155], v[114:129]
	ds_read_b64_tr_b16 v[152:153], v235 offset:0x1400
	ds_read_b64_tr_b16 v[154:155], v235 offset:0x1c00
	s_waitcnt lgkmcnt(6)
	v_mfma_f32_32x32x16_bf16 v[114:129], v[138:141], v[156:159], v[114:129]
	ds_read_b64_tr_b16 v[156:157], v235 offset:0x2400
	ds_read_b64_tr_b16 v[158:159], v235 offset:0x2c00
	s_waitcnt lgkmcnt(6)
	v_mfma_f32_32x32x16_bf16 v[114:129], v[142:145], v[194:197], v[114:129]
	ds_read_b64_tr_b16 v[194:195], v235 offset:0x3400
	ds_read_b64_tr_b16 v[196:197], v235 offset:0x3c00
	s_waitcnt lgkmcnt(6)
	v_mfma_f32_32x32x16_bf16 v[98:113], v[130:133], v[148:151], v[98:113]
	ds_read_b64_tr_b16 v[148:149], v235 offset:0x600
	ds_read_b64_tr_b16 v[150:151], v235 offset:0xe00
	s_waitcnt lgkmcnt(6)
	v_mfma_f32_32x32x16_bf16 v[98:113], v[134:137], v[152:155], v[98:113]
	ds_read_b64_tr_b16 v[152:153], v235 offset:0x1600
	ds_read_b64_tr_b16 v[154:155], v235 offset:0x1e00
	s_waitcnt lgkmcnt(6)
	v_mfma_f32_32x32x16_bf16 v[98:113], v[138:141], v[156:159], v[98:113]
	ds_read_b64_tr_b16 v[156:157], v235 offset:0x2600
	ds_read_b64_tr_b16 v[158:159], v235 offset:0x2e00
	s_waitcnt lgkmcnt(6)
	v_mfma_f32_32x32x16_bf16 v[98:113], v[142:145], v[194:197], v[98:113]
	ds_read_b64_tr_b16 v[194:195], v235 offset:0x3600
	ds_read_b64_tr_b16 v[196:197], v235 offset:0x3e00
	s_waitcnt lgkmcnt(6)
	v_mfma_f32_32x32x16_bf16 v[82:97], v[130:133], v[148:151], v[82:97]
	ds_read_b64_tr_b16 v[148:149], v236 offset:0
	ds_read_b64_tr_b16 v[150:151], v236 offset:0x800
	s_waitcnt lgkmcnt(6)
	v_mfma_f32_32x32x16_bf16 v[82:97], v[134:137], v[152:155], v[82:97]
	ds_read_b64_tr_b16 v[152:153], v236 offset:0x1000
	ds_read_b64_tr_b16 v[154:155], v236 offset:0x1800
	s_waitcnt lgkmcnt(6)
	v_mfma_f32_32x32x16_bf16 v[82:97], v[138:141], v[156:159], v[82:97]
	ds_read_b64_tr_b16 v[156:157], v236 offset:0x2000
	ds_read_b64_tr_b16 v[158:159], v236 offset:0x2800
	s_waitcnt lgkmcnt(6)
	v_mfma_f32_32x32x16_bf16 v[82:97], v[142:145], v[194:197], v[82:97]
	ds_read_b64_tr_b16 v[194:195], v236 offset:0x3000
	ds_read_b64_tr_b16 v[196:197], v236 offset:0x3800
	s_waitcnt lgkmcnt(6)
	v_mfma_f32_32x32x16_bf16 v[66:81], v[130:133], v[148:151], v[66:81]
	ds_read_b64_tr_b16 v[148:149], v236 offset:0x200
	ds_read_b64_tr_b16 v[150:151], v236 offset:0xa00
	s_waitcnt lgkmcnt(6)
	v_mfma_f32_32x32x16_bf16 v[66:81], v[134:137], v[152:155], v[66:81]
	ds_read_b64_tr_b16 v[152:153], v236 offset:0x1200
	ds_read_b64_tr_b16 v[154:155], v236 offset:0x1a00
	s_waitcnt lgkmcnt(6)
	v_mfma_f32_32x32x16_bf16 v[66:81], v[138:141], v[156:159], v[66:81]
	ds_read_b64_tr_b16 v[156:157], v236 offset:0x2200
	ds_read_b64_tr_b16 v[158:159], v236 offset:0x2a00
	s_waitcnt lgkmcnt(6)
	v_mfma_f32_32x32x16_bf16 v[66:81], v[142:145], v[194:197], v[66:81]
	ds_read_b64_tr_b16 v[194:195], v236 offset:0x3200
	ds_read_b64_tr_b16 v[196:197], v236 offset:0x3a00
	s_waitcnt lgkmcnt(6)
	v_mfma_f32_32x32x16_bf16 v[50:65], v[130:133], v[148:151], v[50:65]
	ds_read_b64_tr_b16 v[148:149], v236 offset:0x400
	ds_read_b64_tr_b16 v[150:151], v236 offset:0xc00
	s_waitcnt lgkmcnt(6)
	v_mfma_f32_32x32x16_bf16 v[50:65], v[134:137], v[152:155], v[50:65]
	ds_read_b64_tr_b16 v[152:153], v236 offset:0x1400
	ds_read_b64_tr_b16 v[154:155], v236 offset:0x1c00
	s_waitcnt lgkmcnt(6)
	v_mfma_f32_32x32x16_bf16 v[50:65], v[138:141], v[156:159], v[50:65]
	ds_read_b64_tr_b16 v[156:157], v236 offset:0x2400
	ds_read_b64_tr_b16 v[158:159], v236 offset:0x2c00
	s_waitcnt lgkmcnt(6)
	v_mfma_f32_32x32x16_bf16 v[50:65], v[142:145], v[194:197], v[50:65]
	ds_read_b64_tr_b16 v[194:195], v236 offset:0x3400
	ds_read_b64_tr_b16 v[196:197], v236 offset:0x3c00
	s_waitcnt lgkmcnt(6)
	v_mfma_f32_32x32x16_bf16 v[34:49], v[130:133], v[148:151], v[34:49]
	ds_read_b64_tr_b16 v[148:149], v236 offset:0x600
	ds_read_b64_tr_b16 v[150:151], v236 offset:0xe00
	s_waitcnt lgkmcnt(6)
	v_mfma_f32_32x32x16_bf16 v[34:49], v[134:137], v[152:155], v[34:49]
	ds_read_b64_tr_b16 v[152:153], v236 offset:0x1600
	ds_read_b64_tr_b16 v[154:155], v236 offset:0x1e00
	s_waitcnt lgkmcnt(6)
	v_mfma_f32_32x32x16_bf16 v[34:49], v[138:141], v[156:159], v[34:49]
	ds_read_b64_tr_b16 v[156:157], v236 offset:0x2600
	ds_read_b64_tr_b16 v[158:159], v236 offset:0x2e00
	s_waitcnt lgkmcnt(6)
	v_mfma_f32_32x32x16_bf16 v[34:49], v[142:145], v[194:197], v[34:49]
	ds_read_b64_tr_b16 v[194:195], v236 offset:0x3600
	ds_read_b64_tr_b16 v[196:197], v236 offset:0x3e00
	s_waitcnt lgkmcnt(6)
	v_mfma_f32_32x32x16_bf16 v[18:33], v[130:133], v[148:151], v[18:33]
	s_waitcnt lgkmcnt(4)
	v_mfma_f32_32x32x16_bf16 v[18:33], v[134:137], v[152:155], v[18:33]
	s_waitcnt lgkmcnt(2)
	v_mfma_f32_32x32x16_bf16 v[18:33], v[138:141], v[156:159], v[18:33]
	s_waitcnt lgkmcnt(0)
	v_mfma_f32_32x32x16_bf16 v[18:33], v[142:145], v[194:197], v[18:33]
	s_branch .LBB0_562
.LBB0_581:
	s_barrier
	s_and_saveexec_b64 s[0:1], s[4:5]
	ds_write_b32 v225, v237
	s_or_b64 exec, exec, s[0:1]
	s_waitcnt lgkmcnt(0)
	v_add_u32_e32 v144, s65, v210
	ds_read_b128 v[130:133], v144
	ds_read_b128 v[134:137], v144 offset:32
	s_movk_i32 s0, 0xffc0
	s_movk_i32 s5, 0xc0
	s_mov_b64 s[72:73], 0x100
	s_waitcnt lgkmcnt(0)
	v_rcp_f32_e32 v138, v130
	v_rcp_f32_e32 v139, v131
	v_rcp_f32_e32 v140, v132
	v_rcp_f32_e32 v141, v133
	v_rcp_f32_e32 v142, v136
	v_pk_mul_f32 v[130:131], v[2:3], v[138:139]
	v_pk_mul_f32 v[114:115], v[114:115], v[138:139]
	v_pk_mul_f32 v[98:99], v[98:99], v[138:139]
	v_pk_mul_f32 v[82:83], v[82:83], v[138:139]
	v_pk_mul_f32 v[66:67], v[66:67], v[138:139]
	v_pk_mul_f32 v[50:51], v[50:51], v[138:139]
	v_pk_mul_f32 v[34:35], v[34:35], v[138:139]
	v_pk_mul_f32 v[2:3], v[18:19], v[138:139]
	v_rcp_f32_e32 v138, v134
	v_rcp_f32_e32 v139, v135
	v_pk_mul_f32 v[132:133], v[4:5], v[140:141]
	v_pk_mul_f32 v[4:5], v[20:21], v[140:141]
	v_pk_mul_f32 v[116:117], v[116:117], v[140:141]
	v_pk_mul_f32 v[134:135], v[6:7], v[138:139]
	v_pk_mul_f32 v[6:7], v[22:23], v[138:139]
	ds_read_b128 v[20:23], v144 offset:64
	v_pk_mul_f32 v[100:101], v[100:101], v[140:141]
	v_pk_mul_f32 v[84:85], v[84:85], v[140:141]
	v_pk_mul_f32 v[68:69], v[68:69], v[140:141]
	v_pk_mul_f32 v[52:53], v[52:53], v[140:141]
	v_pk_mul_f32 v[36:37], v[36:37], v[140:141]
	v_pk_mul_f32 v[118:119], v[118:119], v[138:139]
	v_pk_mul_f32 v[102:103], v[102:103], v[138:139]
	v_pk_mul_f32 v[86:87], v[86:87], v[138:139]
	v_pk_mul_f32 v[70:71], v[70:71], v[138:139]
	v_pk_mul_f32 v[54:55], v[54:55], v[138:139]
	v_pk_mul_f32 v[18:19], v[38:39], v[138:139]
	ds_read_b128 v[138:141], v144 offset:96
	v_rcp_f32_e32 v143, v137
	s_waitcnt lgkmcnt(0)
	v_rcp_f32_e32 v144, v20
	v_rcp_f32_e32 v145, v21
	v_rcp_f32_e32 v22, v22
	v_rcp_f32_e32 v23, v23
	v_pk_mul_f32 v[20:21], v[40:41], v[142:143]
	v_pk_mul_f32 v[38:39], v[106:107], v[144:145]
	v_pk_mul_f32 v[106:107], v[26:27], v[144:145]
	v_pk_mul_f32 v[12:13], v[12:13], v[22:23]
	v_pk_mul_f32 v[26:27], v[124:125], v[22:23]
	v_pk_mul_f32 v[40:41], v[108:109], v[22:23]
	v_pk_mul_f32 v[92:93], v[92:93], v[22:23]
	v_pk_mul_f32 v[76:77], v[76:77], v[22:23]
	v_rcp_f32_e32 v138, v138
	v_rcp_f32_e32 v139, v139
	v_pk_mul_f32 v[60:61], v[60:61], v[22:23]
	v_pk_mul_f32 v[44:45], v[44:45], v[22:23]
	v_pk_mul_f32 v[108:109], v[28:29], v[22:23]
	v_rcp_f32_e32 v22, v140
	v_rcp_f32_e32 v23, v141
	v_pk_mul_f32 v[28:29], v[110:111], v[138:139]
	v_pk_mul_f32 v[110:111], v[30:31], v[138:139]
	v_pk_mul_f32 v[10:11], v[10:11], v[144:145]
	v_pk_mul_f32 v[16:17], v[16:17], v[22:23]
	v_pk_mul_f32 v[124:125], v[128:129], v[22:23]
	v_pk_mul_f32 v[30:31], v[112:113], v[22:23]
	v_pk_mul_f32 v[96:97], v[96:97], v[22:23]
	v_pk_mul_f32 v[80:81], v[80:81], v[22:23]
	v_pk_mul_f32 v[64:65], v[64:65], v[22:23]
	v_pk_mul_f32 v[48:49], v[48:49], v[22:23]
	v_pk_mul_f32 v[112:113], v[32:33], v[22:23]
	v_mov_b32_e32 v22, v0
	v_pk_mul_f32 v[136:137], v[8:9], v[142:143]
	v_ashrrev_i32_e32 v23, 31, v22
	v_lshl_add_u64 v[22:23], s[30:31], 0, v[22:23]
	v_lshlrev_b64 v[22:23], 9, v[22:23]
	v_lshl_add_u64 v[22:23], s[28:29], 0, v[22:23]
	v_pk_mul_f32 v[120:121], v[120:121], v[142:143]
	v_pk_mul_f32 v[104:105], v[104:105], v[142:143]
	v_pk_mul_f32 v[88:89], v[88:89], v[142:143]
	v_pk_mul_f32 v[72:73], v[72:73], v[142:143]
	v_pk_mul_f32 v[56:57], v[56:57], v[142:143]
	v_pk_mul_f32 v[8:9], v[24:25], v[142:143]
	v_pk_mul_f32 v[24:25], v[122:123], v[144:145]
	v_pk_mul_f32 v[90:91], v[90:91], v[144:145]
	v_pk_mul_f32 v[74:75], v[74:75], v[144:145]
	v_pk_mul_f32 v[58:59], v[58:59], v[144:145]
	v_pk_mul_f32 v[42:43], v[42:43], v[144:145]
	v_pk_mul_f32 v[14:15], v[14:15], v[138:139]
	v_pk_mul_f32 v[122:123], v[126:127], v[138:139]
	v_pk_mul_f32 v[94:95], v[94:95], v[138:139]
	v_pk_mul_f32 v[78:79], v[78:79], v[138:139]
	v_pk_mul_f32 v[62:63], v[62:63], v[138:139]
	v_pk_mul_f32 v[46:47], v[46:47], v[138:139]
	global_store_dwordx4 v[22:23], v[130:133], off
	global_store_dwordx4 v[22:23], v[134:137], off offset:16
	global_store_dwordx4 v[22:23], v[10:13], off offset:32
	global_store_dwordx4 v[22:23], v[14:17], off offset:48
	global_store_dwordx4 v[22:23], v[114:117], off offset:64
	global_store_dwordx4 v[22:23], v[118:121], off offset:80
	global_store_dwordx4 v[22:23], v[24:27], off offset:96
	global_store_dwordx4 v[22:23], v[122:125], off offset:112
	global_store_dwordx4 v[22:23], v[98:101], off offset:128
	global_store_dwordx4 v[22:23], v[102:105], off offset:144
	global_store_dwordx4 v[22:23], v[38:41], off offset:160
	global_store_dwordx4 v[22:23], v[28:31], off offset:176
	global_store_dwordx4 v[22:23], v[82:85], off offset:192
	global_store_dwordx4 v[22:23], v[86:89], off offset:208
	global_store_dwordx4 v[22:23], v[90:93], off offset:224
	global_store_dwordx4 v[22:23], v[94:97], off offset:240
	global_store_dwordx4 v[22:23], v[66:69], off offset:256
	global_store_dwordx4 v[22:23], v[70:73], off offset:272
	global_store_dwordx4 v[22:23], v[74:77], off offset:288
	global_store_dwordx4 v[22:23], v[78:81], off offset:304
	global_store_dwordx4 v[22:23], v[50:53], off offset:320
	global_store_dwordx4 v[22:23], v[54:57], off offset:336
	global_store_dwordx4 v[22:23], v[58:61], off offset:352
	global_store_dwordx4 v[22:23], v[62:65], off offset:368
	global_store_dwordx4 v[22:23], v[34:37], off offset:384
	global_store_dwordx4 v[22:23], v[18:21], off offset:400
	global_store_dwordx4 v[22:23], v[42:45], off offset:416
	global_store_dwordx4 v[22:23], v[46:49], off offset:432
	global_store_dwordx4 v[22:23], v[2:5], off offset:448
	global_store_dwordx4 v[22:23], v[6:9], off offset:464
	global_store_dwordx4 v[22:23], v[106:109], off offset:480
	global_store_dwordx4 v[22:23], v[110:113], off offset:496
	v_mov_b32_e32 v10, v0
	v_mov_b32_e32 v237, 0
	v_readfirstlane_b32 s6, v10
	v_and_b32_e32 v11, 63, v10
	v_lshrrev_b32_e32 v13, 1, v10
	v_mov_b32_e32 v2, s6
	v_bfi_b32 v2, s0, v2, v10
	s_ashr_i32 s0, s6, 4
	s_and_b32 s7, s0, 0xffff0
	s_lshr_b32 s0, s0, 1
	s_and_b32 s14, s0, 4
	s_or_b32 s0, s14, s7
	v_and_b32_e32 v14, 8, v13
	v_bfe_u32 v15, v10, 2, 2
	v_lshlrev_b32_e32 v16, 4, v11
	v_and_b32_e32 v12, 31, v10
	v_ashrrev_i32_e32 v3, 4, v2
	v_or3_b32 v8, s0, v15, v14
	v_lshlrev_b32_e32 v2, 1, v2
	v_and_b32_e32 v17, 48, v16
	s_ashr_i32 s0, s6, 6
	v_and_b32_e32 v4, 15, v10
	v_and_or_b32 v9, v2, s5, v17
	v_lshl_or_b32 v2, s0, 5, v12
	v_bitop3_b32 v4, v3, v4, 7 bitop3:0x6c
	v_lshlrev_b32_e32 v5, 12, v3
	v_ashrrev_i32_e32 v3, 31, v2
	v_lshlrev_b64 v[2:3], 12, v[2:3]
	v_lshl_add_u64 v[2:3], s[40:41], 0, v[2:3]
	v_and_b32_e32 v210, 16, v13
	v_lshl_add_u64 v[2:3], v[2:3], 0, v[210:211]
	global_load_dwordx4 v[162:165], v[2:3], off offset:256
	global_load_dwordx4 v[166:169], v[2:3], off offset:288
	global_load_dwordx4 v[170:173], v[2:3], off offset:320
	global_load_dwordx4 v[174:177], v[2:3], off offset:352
	global_load_dwordx4 v[178:181], v[2:3], off offset:384
	global_load_dwordx4 v[182:185], v[2:3], off offset:416
	global_load_dwordx4 v[186:189], v[2:3], off offset:448
	global_load_dwordx4 v[190:193], v[2:3], off offset:480
	v_lshl_or_b32 v2, v4, 4, v5
	v_mov_b32_e32 v3, v211
	s_lshl_b32 s4, s0, 10
	v_lshl_add_u64 v[4:5], s[38:39], 0, v[2:3]
	s_add_i32 s38, s4, 0
	v_lshl_add_u64 v[6:7], v[4:5], 0, s[72:73]
	s_mov_b32 m0, s38
	s_mov_b64 s[0:1], 0x20100
	s_add_i32 s39, s38, 0x2000
	global_load_lds_dwordx4 v[6:7], off
	v_lshl_add_u64 v[6:7], v[4:5], 0, s[0:1]
	s_mov_b32 m0, s39
	s_add_i32 s40, s38, 0x8000
	global_load_lds_dwordx4 v[6:7], off
	v_lshl_or_b32 v6, v8, 12, v9
	v_mov_b32_e32 v7, v211
	s_mov_b32 m0, s40
	v_lshl_add_u64 v[8:9], s[36:37], 0, v[6:7]
	global_load_lds_dwordx4 v6, s[36:37]
	s_add_i32 s36, s38, 0xa000
	s_mov_b32 m0, s36
	s_add_i32 s37, s38, 0xc000
	global_load_lds_dwordx4 v6, s[42:43]
	v_lshl_add_u64 v[8:9], v[8:9], 0, s[72:73]
	s_mov_b32 m0, s37
	s_add_i32 s41, s38, 0xe000
	global_load_lds_dwordx4 v[8:9], off
	s_mov_b32 m0, s41
	s_mov_b64 s[0:1], 0x40100
	s_add_i32 s42, s38, 0x4000
	global_load_lds_dwordx4 v6, s[50:51]
	v_lshl_add_u64 v[8:9], v[4:5], 0, s[0:1]
	s_mov_b32 m0, s42
	s_mov_b64 s[0:1], 0x60100
	s_add_i32 s43, s38, 0x6000
	global_load_lds_dwordx4 v[8:9], off
	v_lshl_add_u64 v[4:5], v[4:5], 0, s[0:1]
	s_mov_b32 m0, s43
	s_add_i32 s0, s33, s4
	global_load_lds_dwordx4 v[4:5], off
	s_mov_b32 m0, s0
	v_lshlrev_b32_e32 v4, 3, v11
	global_load_lds_dwordx4 v6, s[52:53]
	s_add_i32 m0, s0, 0x2000
	v_and_b32_e32 v5, 0xc0, v16
	global_load_lds_dwordx4 v6, s[68:69]
	s_add_i32 m0, s0, 0x4000
	v_and_or_b32 v5, v4, 24, v5
	global_load_lds_dwordx4 v6, s[84:85]
	s_add_i32 m0, s0, 0x6000
	s_and_b32 s0, s6, 0xffffffc0
	global_load_lds_dwordx4 v6, s[86:87]
	v_lshlrev_b32_e32 v6, 1, v11
	v_and_b32_e32 v7, 32, v6
	v_and_b32_e32 v4, 0x100, v4
	s_lshl_b32 s0, s0, 2
	v_or3_b32 v4, v5, v7, v4
	v_lshlrev_b32_e32 v5, 4, v10
	s_add_i32 s50, s0, 0
	v_and_b32_e32 v5, 0x70, v5
	s_movk_i32 s0, 0x60
	v_bitop3_b32 v22, v210, v5, s0 bitop3:0x36
	s_movk_i32 s0, 0x80
	v_bitop3_b32 v23, v210, v5, s0 bitop3:0x36
	s_movk_i32 s0, 0xa0
	v_bitop3_b32 v24, v210, v5, s0 bitop3:0x36
	s_movk_i32 s0, 0xe0
	v_bitop3_b32 v26, v210, v5, s0 bitop3:0x36
	v_lshl_add_u64 v[216:217], s[34:35], 0, v[2:3]
	v_or_b32_e32 v2, s7, v14
	s_lshl_b32 s0, s6, 1
	v_or3_b32 v2, v2, s14, v15
	s_and_b32 s0, s0, 0xffffff80
	v_lshlrev_b32_e32 v2, 12, v2
	v_bitop3_b32 v3, s0, v231, v6 bitop3:0xc8
	s_add_i32 s50, s50, 0x18000
	v_lshl_add_u32 v18, v12, 8, 0
	v_bitop3_b32 v19, v13, v5, 16 bitop3:0x6c
	v_bitop3_b32 v20, v210, v5, 32 bitop3:0x36
	v_bitop3_b32 v21, v210, v5, 64 bitop3:0x36
	v_bitop3_b32 v25, v210, v5, s5 bitop3:0x36
	v_or3_b32 v2, v2, v3, v17
	v_mov_b32_e32 v3, v211
	v_mov_b32_e32 v16, v211
	v_mov_b32_e32 v17, v211
	v_add_u32_e32 v224, s21, v4
	v_cmp_gt_u32_e64 s[4:5], 32, v11
	v_lshl_add_u32 v225, v12, 2, s50
	v_add_u32_e32 v234, s57, v4
	v_add_u32_e32 v235, s33, v4
	v_add_u32_e32 v236, s61, v4
	v_lshl_add_u64 v[218:219], s[2:3], 0, v[2:3]
	v_mov_b32_e32 v2, v211
	v_mov_b32_e32 v4, v211
	v_mov_b32_e32 v5, v211
	v_mov_b32_e32 v6, v211
	v_mov_b32_e32 v7, v211
	v_mov_b32_e32 v8, v211
	v_mov_b32_e32 v9, v211
	v_mov_b32_e32 v10, v211
	v_mov_b32_e32 v11, v211
	v_mov_b32_e32 v12, v211
	v_mov_b32_e32 v13, v211
	v_mov_b32_e32 v14, v211
	v_mov_b32_e32 v15, v211
	v_add_u32_e32 v238, v18, v19
	v_add_u32_e32 v239, v18, v20
	v_add_u32_e32 v240, v18, v21
	v_add_u32_e32 v241, v18, v22
	v_add_u32_e32 v242, v18, v23
	v_add_u32_e32 v243, v18, v24
	v_add_u32_e32 v244, v18, v25
	v_add_u32_e32 v245, v18, v26
	v_mov_b64_e32 v[32:33], v[16:17]
	v_mov_b64_e32 v[48:49], v[16:17]
	v_mov_b64_e32 v[64:65], v[16:17]
	v_mov_b64_e32 v[80:81], v[16:17]
	v_mov_b64_e32 v[96:97], v[16:17]
	v_mov_b64_e32 v[112:113], v[16:17]
	v_mov_b64_e32 v[128:129], v[16:17]
	s_mov_b32 s51, 3
	v_mov_b32_e32 v249, 0xf149f2ca
	v_mov_b64_e32 v[30:31], v[14:15]
	v_mov_b64_e32 v[28:29], v[12:13]
	v_mov_b64_e32 v[26:27], v[10:11]
	v_mov_b64_e32 v[24:25], v[8:9]
	v_mov_b64_e32 v[22:23], v[6:7]
	v_mov_b64_e32 v[20:21], v[4:5]
	v_mov_b64_e32 v[18:19], v[2:3]
	v_mov_b64_e32 v[46:47], v[14:15]
	v_mov_b64_e32 v[44:45], v[12:13]
	v_mov_b64_e32 v[42:43], v[10:11]
	v_mov_b64_e32 v[40:41], v[8:9]
	v_mov_b64_e32 v[38:39], v[6:7]
	v_mov_b64_e32 v[36:37], v[4:5]
	v_mov_b64_e32 v[34:35], v[2:3]
	v_mov_b64_e32 v[62:63], v[14:15]
	v_mov_b64_e32 v[60:61], v[12:13]
	v_mov_b64_e32 v[58:59], v[10:11]
	v_mov_b64_e32 v[56:57], v[8:9]
	v_mov_b64_e32 v[54:55], v[6:7]
	v_mov_b64_e32 v[52:53], v[4:5]
	v_mov_b64_e32 v[50:51], v[2:3]
	v_mov_b64_e32 v[78:79], v[14:15]
	v_mov_b64_e32 v[76:77], v[12:13]
	v_mov_b64_e32 v[74:75], v[10:11]
	v_mov_b64_e32 v[72:73], v[8:9]
	v_mov_b64_e32 v[70:71], v[6:7]
	v_mov_b64_e32 v[68:69], v[4:5]
	v_mov_b64_e32 v[66:67], v[2:3]
	v_mov_b64_e32 v[94:95], v[14:15]
	v_mov_b64_e32 v[92:93], v[12:13]
	v_mov_b64_e32 v[90:91], v[10:11]
	v_mov_b64_e32 v[88:89], v[8:9]
	v_mov_b64_e32 v[86:87], v[6:7]
	v_mov_b64_e32 v[84:85], v[4:5]
	v_mov_b64_e32 v[82:83], v[2:3]
	v_mov_b64_e32 v[110:111], v[14:15]
	v_mov_b64_e32 v[108:109], v[12:13]
	v_mov_b64_e32 v[106:107], v[10:11]
	v_mov_b64_e32 v[104:105], v[8:9]
	v_mov_b64_e32 v[102:103], v[6:7]
	v_mov_b64_e32 v[100:101], v[4:5]
	v_mov_b64_e32 v[98:99], v[2:3]
	v_mov_b64_e32 v[126:127], v[14:15]
	v_mov_b64_e32 v[124:125], v[12:13]
	v_mov_b64_e32 v[122:123], v[10:11]
	v_mov_b64_e32 v[120:121], v[8:9]
	v_mov_b64_e32 v[118:119], v[6:7]
	v_mov_b64_e32 v[116:117], v[4:5]
	v_mov_b64_e32 v[114:115], v[2:3]
	s_mov_b32 s76, 0xbf3a00e3
	s_mov_b32 s75, s15
	s_waitcnt vmcnt(0)
	s_branch .LBB0_585

.LBB0_593:
	v_cndmask_b32_e64 v249, v220, v249, s[6:7]
	v_mul_f32_e32 v194, 0xbe0293ee, v249
	v_fmamk_f32 v146, v146, 0x3e0293ee, v194
	v_fmamk_f32 v147, v147, 0x3e0293ee, v194
	v_fmamk_f32 v148, v148, 0x3e0293ee, v194
	v_fmamk_f32 v149, v149, 0x3e0293ee, v194
	v_fmamk_f32 v150, v150, 0x3e0293ee, v194
	v_fmamk_f32 v151, v151, 0x3e0293ee, v194
	v_fmamk_f32 v152, v152, 0x3e0293ee, v194
	v_fmamk_f32 v153, v153, 0x3e0293ee, v194
	v_fmamk_f32 v154, v154, 0x3e0293ee, v194
	v_fmamk_f32 v155, v155, 0x3e0293ee, v194
	v_fmamk_f32 v156, v156, 0x3e0293ee, v194
	v_fmamk_f32 v157, v157, 0x3e0293ee, v194
	v_fmamk_f32 v158, v158, 0x3e0293ee, v194
	v_fmamk_f32 v159, v159, 0x3e0293ee, v194
	v_fmamk_f32 v160, v160, 0x3e0293ee, v194
	v_fmamk_f32 v161, v161, 0x3e0293ee, v194
	v_fmamk_f32 v130, v130, 0x3e0293ee, v194
	v_fmamk_f32 v131, v131, 0x3e0293ee, v194
	v_fmamk_f32 v132, v132, 0x3e0293ee, v194
	v_fmamk_f32 v133, v133, 0x3e0293ee, v194
	v_fmamk_f32 v134, v134, 0x3e0293ee, v194
	v_fmamk_f32 v135, v135, 0x3e0293ee, v194
	v_fmamk_f32 v136, v136, 0x3e0293ee, v194
	v_fmamk_f32 v137, v137, 0x3e0293ee, v194
	v_fmamk_f32 v138, v138, 0x3e0293ee, v194
	v_fmamk_f32 v139, v139, 0x3e0293ee, v194
	v_fmamk_f32 v140, v140, 0x3e0293ee, v194
	v_fmamk_f32 v141, v141, 0x3e0293ee, v194
	v_fmamk_f32 v142, v142, 0x3e0293ee, v194
	v_fmamk_f32 v143, v143, 0x3e0293ee, v194
	v_fmamk_f32 v144, v144, 0x3e0293ee, v194
	v_fmac_f32_e32 v194, 0x3e0293ee, v145
	v_exp_f32_e32 v145, v146
	v_exp_f32_e32 v146, v147
	v_exp_f32_e32 v147, v148
	v_exp_f32_e32 v148, v149
	v_exp_f32_e32 v149, v150
	v_exp_f32_e32 v150, v151
	v_exp_f32_e32 v151, v152
	v_exp_f32_e32 v152, v153
	v_exp_f32_e32 v153, v154
	v_exp_f32_e32 v154, v155
	v_exp_f32_e32 v155, v156
	v_exp_f32_e32 v156, v157
	v_exp_f32_e32 v157, v158
	v_exp_f32_e32 v158, v159
	v_exp_f32_e32 v159, v160
	v_exp_f32_e32 v160, v161
	v_exp_f32_e32 v161, v130
	v_add_f32_e32 v130, 0, v145
	v_add_f32_e32 v130, v146, v130
	v_add_f32_e32 v130, v147, v130
	v_add_f32_e32 v130, v148, v130
	v_add_f32_e32 v130, v149, v130
	v_add_f32_e32 v130, v150, v130
	v_add_f32_e32 v130, v151, v130
	v_add_f32_e32 v130, v152, v130
	v_add_f32_e32 v130, v153, v130
	v_add_f32_e32 v130, v154, v130
	v_add_f32_e32 v130, v155, v130
	v_add_f32_e32 v130, v156, v130
	v_add_f32_e32 v130, v157, v130
	v_exp_f32_e32 v195, v131
	v_add_f32_e32 v130, v158, v130
	v_exp_f32_e32 v196, v132
	v_add_f32_e32 v130, v159, v130
	v_exp_f32_e32 v197, v133
	v_add_f32_e32 v130, v160, v130
	v_exp_f32_e32 v198, v134
	v_add_f32_e32 v130, v161, v130
	v_exp_f32_e32 v199, v135
	v_add_f32_e32 v130, v195, v130
	v_exp_f32_e32 v200, v136
	v_add_f32_e32 v130, v196, v130
	v_exp_f32_e32 v201, v137
	v_add_f32_e32 v130, v197, v130
	v_exp_f32_e32 v202, v138
	v_add_f32_e32 v130, v198, v130
	v_exp_f32_e32 v203, v139
	v_add_f32_e32 v130, v199, v130
	v_exp_f32_e32 v204, v140
	v_add_f32_e32 v130, v200, v130
	v_exp_f32_e32 v205, v141
	v_add_f32_e32 v130, v201, v130
	v_exp_f32_e32 v206, v142
	v_add_f32_e32 v130, v202, v130
	v_exp_f32_e32 v207, v143
	v_add_f32_e32 v130, v203, v130
	v_exp_f32_e32 v208, v144
	v_add_f32_e32 v130, v204, v130
	v_exp_f32_e32 v194, v194
	v_add_f32_e32 v130, v205, v130
	v_add_f32_e32 v130, v206, v130
	v_add_f32_e32 v130, v207, v130
	v_add_f32_e32 v130, v208, v130
	v_add_f32_e32 v247, v194, v130
	v_mov_b32_e32 v248, v247
	s_nop 1
	v_permlane32_swap_b32_e32 v247, v248
	v_cvt_pk_bf16_f32 v130, v145, v146
	v_cvt_pk_bf16_f32 v131, v147, v148
	v_cvt_pk_bf16_f32 v132, v149, v150
	v_cvt_pk_bf16_f32 v133, v151, v152
	v_cvt_pk_bf16_f32 v134, v153, v154
	v_cvt_pk_bf16_f32 v135, v155, v156
	v_cvt_pk_bf16_f32 v136, v157, v158
	v_cvt_pk_bf16_f32 v137, v159, v160
	v_cvt_pk_bf16_f32 v138, v161, v195
	v_cvt_pk_bf16_f32 v139, v196, v197
	v_cvt_pk_bf16_f32 v140, v198, v199
	v_cvt_pk_bf16_f32 v141, v200, v201
	v_cvt_pk_bf16_f32 v142, v202, v203
	v_cvt_pk_bf16_f32 v143, v204, v205
	v_cvt_pk_bf16_f32 v144, v206, v207
	v_cvt_pk_bf16_f32 v145, v208, v194
	s_nop 0
	v_permlane32_swap_b32_e32 v130, v132
	v_permlane32_swap_b32_e32 v131, v133
	v_permlane32_swap_b32_e32 v134, v136
	v_permlane32_swap_b32_e32 v135, v137
	v_permlane32_swap_b32_e32 v138, v140
	v_permlane32_swap_b32_e32 v139, v141
	v_permlane32_swap_b32_e32 v142, v144
	v_permlane32_swap_b32_e32 v143, v145
	ds_read_b64_tr_b16 v[146:147], v224 offset:0
	ds_read_b64_tr_b16 v[148:149], v224 offset:0x800
	ds_read_b64_tr_b16 v[150:151], v224 offset:0x1000
	ds_read_b64_tr_b16 v[152:153], v224 offset:0x1800
	ds_read_b64_tr_b16 v[154:155], v224 offset:0x2000
	ds_read_b64_tr_b16 v[156:157], v224 offset:0x2800
	ds_read_b64_tr_b16 v[158:159], v224 offset:0x3000
	ds_read_b64_tr_b16 v[160:161], v224 offset:0x3800
	s_nop 0
	s_waitcnt lgkmcnt(6)
	v_mfma_f32_32x32x16_bf16 v[2:17], v[130:133], v[146:149], v[2:17]
	ds_read_b64_tr_b16 v[146:147], v224 offset:0x200
	ds_read_b64_tr_b16 v[148:149], v224 offset:0xa00
	s_waitcnt lgkmcnt(6)
	v_mfma_f32_32x32x16_bf16 v[2:17], v[134:137], v[150:153], v[2:17]
	ds_read_b64_tr_b16 v[150:151], v224 offset:0x1200
	ds_read_b64_tr_b16 v[152:153], v224 offset:0x1a00
	s_waitcnt lgkmcnt(6)
	v_mfma_f32_32x32x16_bf16 v[2:17], v[138:141], v[154:157], v[2:17]
	ds_read_b64_tr_b16 v[154:155], v224 offset:0x2200
	ds_read_b64_tr_b16 v[156:157], v224 offset:0x2a00
	s_waitcnt lgkmcnt(6)
	v_mfma_f32_32x32x16_bf16 v[2:17], v[142:145], v[158:161], v[2:17]
	ds_read_b64_tr_b16 v[158:159], v224 offset:0x3200
	ds_read_b64_tr_b16 v[160:161], v224 offset:0x3a00
	s_waitcnt lgkmcnt(6)
	v_mfma_f32_32x32x16_bf16 v[18:33], v[130:133], v[146:149], v[18:33]
	ds_read_b64_tr_b16 v[146:147], v224 offset:0x400
	ds_read_b64_tr_b16 v[148:149], v224 offset:0xc00
	s_waitcnt lgkmcnt(6)
	v_mfma_f32_32x32x16_bf16 v[18:33], v[134:137], v[150:153], v[18:33]
	ds_read_b64_tr_b16 v[150:151], v224 offset:0x1400
	ds_read_b64_tr_b16 v[152:153], v224 offset:0x1c00
	s_waitcnt lgkmcnt(6)
	v_mfma_f32_32x32x16_bf16 v[18:33], v[138:141], v[154:157], v[18:33]
	ds_read_b64_tr_b16 v[154:155], v224 offset:0x2400
	ds_read_b64_tr_b16 v[156:157], v224 offset:0x2c00
	s_waitcnt lgkmcnt(6)
	v_mfma_f32_32x32x16_bf16 v[18:33], v[142:145], v[158:161], v[18:33]
	ds_read_b64_tr_b16 v[158:159], v224 offset:0x3400
	ds_read_b64_tr_b16 v[160:161], v224 offset:0x3c00
	s_waitcnt lgkmcnt(6)
	v_mfma_f32_32x32x16_bf16 v[34:49], v[130:133], v[146:149], v[34:49]
	ds_read_b64_tr_b16 v[146:147], v224 offset:0x600
	ds_read_b64_tr_b16 v[148:149], v224 offset:0xe00
	s_waitcnt lgkmcnt(6)
	v_mfma_f32_32x32x16_bf16 v[34:49], v[134:137], v[150:153], v[34:49]
	ds_read_b64_tr_b16 v[150:151], v224 offset:0x1600
	ds_read_b64_tr_b16 v[152:153], v224 offset:0x1e00
	s_waitcnt lgkmcnt(6)
	v_mfma_f32_32x32x16_bf16 v[34:49], v[138:141], v[154:157], v[34:49]
	ds_read_b64_tr_b16 v[154:155], v224 offset:0x2600
	ds_read_b64_tr_b16 v[156:157], v224 offset:0x2e00
	s_waitcnt lgkmcnt(6)
	v_mfma_f32_32x32x16_bf16 v[34:49], v[142:145], v[158:161], v[34:49]
	ds_read_b64_tr_b16 v[158:159], v224 offset:0x3600
	ds_read_b64_tr_b16 v[160:161], v224 offset:0x3e00
	s_waitcnt lgkmcnt(6)
	v_mfma_f32_32x32x16_bf16 v[50:65], v[130:133], v[146:149], v[50:65]
	ds_read_b64_tr_b16 v[146:147], v234 offset:0
	ds_read_b64_tr_b16 v[148:149], v234 offset:0x800
	s_waitcnt lgkmcnt(6)
	v_mfma_f32_32x32x16_bf16 v[50:65], v[134:137], v[150:153], v[50:65]
	ds_read_b64_tr_b16 v[150:151], v234 offset:0x1000
	ds_read_b64_tr_b16 v[152:153], v234 offset:0x1800
	s_waitcnt lgkmcnt(6)
	v_mfma_f32_32x32x16_bf16 v[50:65], v[138:141], v[154:157], v[50:65]
	ds_read_b64_tr_b16 v[154:155], v234 offset:0x2000
	ds_read_b64_tr_b16 v[156:157], v234 offset:0x2800
	s_waitcnt lgkmcnt(6)
	v_mfma_f32_32x32x16_bf16 v[50:65], v[142:145], v[158:161], v[50:65]
	ds_read_b64_tr_b16 v[158:159], v234 offset:0x3000
	ds_read_b64_tr_b16 v[160:161], v234 offset:0x3800
	s_waitcnt lgkmcnt(6)
	v_mfma_f32_32x32x16_bf16 v[66:81], v[130:133], v[146:149], v[66:81]
	ds_read_b64_tr_b16 v[146:147], v234 offset:0x200
	ds_read_b64_tr_b16 v[148:149], v234 offset:0xa00
	s_waitcnt lgkmcnt(6)
	v_mfma_f32_32x32x16_bf16 v[66:81], v[134:137], v[150:153], v[66:81]
	ds_read_b64_tr_b16 v[150:151], v234 offset:0x1200
	ds_read_b64_tr_b16 v[152:153], v234 offset:0x1a00
	s_waitcnt lgkmcnt(6)
	v_mfma_f32_32x32x16_bf16 v[66:81], v[138:141], v[154:157], v[66:81]
	ds_read_b64_tr_b16 v[154:155], v234 offset:0x2200
	ds_read_b64_tr_b16 v[156:157], v234 offset:0x2a00
	s_waitcnt lgkmcnt(6)
	v_mfma_f32_32x32x16_bf16 v[66:81], v[142:145], v[158:161], v[66:81]
	ds_read_b64_tr_b16 v[158:159], v234 offset:0x3200
	ds_read_b64_tr_b16 v[160:161], v234 offset:0x3a00
	s_waitcnt lgkmcnt(6)
	v_mfma_f32_32x32x16_bf16 v[82:97], v[130:133], v[146:149], v[82:97]
	ds_read_b64_tr_b16 v[146:147], v234 offset:0x400
	ds_read_b64_tr_b16 v[148:149], v234 offset:0xc00
	s_waitcnt lgkmcnt(6)
	v_mfma_f32_32x32x16_bf16 v[82:97], v[134:137], v[150:153], v[82:97]
	ds_read_b64_tr_b16 v[150:151], v234 offset:0x1400
	ds_read_b64_tr_b16 v[152:153], v234 offset:0x1c00
	s_waitcnt lgkmcnt(6)
	v_mfma_f32_32x32x16_bf16 v[82:97], v[138:141], v[154:157], v[82:97]
	ds_read_b64_tr_b16 v[154:155], v234 offset:0x2400
	ds_read_b64_tr_b16 v[156:157], v234 offset:0x2c00
	s_waitcnt lgkmcnt(6)
	v_mfma_f32_32x32x16_bf16 v[82:97], v[142:145], v[158:161], v[82:97]
	ds_read_b64_tr_b16 v[158:159], v234 offset:0x3400
	ds_read_b64_tr_b16 v[160:161], v234 offset:0x3c00
	s_waitcnt lgkmcnt(6)
	v_mfma_f32_32x32x16_bf16 v[98:113], v[130:133], v[146:149], v[98:113]
	ds_read_b64_tr_b16 v[146:147], v234 offset:0x600
	ds_read_b64_tr_b16 v[148:149], v234 offset:0xe00
	s_waitcnt lgkmcnt(6)
	v_mfma_f32_32x32x16_bf16 v[98:113], v[134:137], v[150:153], v[98:113]
	ds_read_b64_tr_b16 v[150:151], v234 offset:0x1600
	ds_read_b64_tr_b16 v[152:153], v234 offset:0x1e00
	s_waitcnt lgkmcnt(6)
	v_mfma_f32_32x32x16_bf16 v[98:113], v[138:141], v[154:157], v[98:113]
	ds_read_b64_tr_b16 v[154:155], v234 offset:0x2600
	ds_read_b64_tr_b16 v[156:157], v234 offset:0x2e00
	s_waitcnt lgkmcnt(6)
	v_mfma_f32_32x32x16_bf16 v[98:113], v[142:145], v[158:161], v[98:113]
	ds_read_b64_tr_b16 v[158:159], v234 offset:0x3600
	ds_read_b64_tr_b16 v[160:161], v234 offset:0x3e00
	s_waitcnt lgkmcnt(6)
	v_mfma_f32_32x32x16_bf16 v[114:129], v[130:133], v[146:149], v[114:129]
	s_waitcnt lgkmcnt(4)
	v_mfma_f32_32x32x16_bf16 v[114:129], v[134:137], v[150:153], v[114:129]
	s_waitcnt lgkmcnt(2)
	v_mfma_f32_32x32x16_bf16 v[114:129], v[138:141], v[154:157], v[114:129]
	s_waitcnt lgkmcnt(0)
	v_mfma_f32_32x32x16_bf16 v[114:129], v[142:145], v[158:161], v[114:129]
	s_add_i32 s2, s51, -1
	v_lshl_add_u64 v[222:223], v[216:217], 0, s[44:45]
	v_lshl_add_u64 v[220:221], v[218:219], 0, s[44:45]
	s_waitcnt vmcnt(0)

.LBB0_601:
	v_cndmask_b32_e64 v249, v251, v249, s[6:7]
	v_mul_f32_e32 v194, 0xbe0293ee, v249
	v_fmamk_f32 v146, v146, 0x3e0293ee, v194
	v_fmamk_f32 v147, v147, 0x3e0293ee, v194
	v_fmamk_f32 v148, v148, 0x3e0293ee, v194
	v_fmamk_f32 v149, v149, 0x3e0293ee, v194
	v_fmamk_f32 v150, v150, 0x3e0293ee, v194
	v_fmamk_f32 v151, v151, 0x3e0293ee, v194
	v_fmamk_f32 v152, v152, 0x3e0293ee, v194
	v_fmamk_f32 v153, v153, 0x3e0293ee, v194
	v_fmamk_f32 v154, v154, 0x3e0293ee, v194
	v_fmamk_f32 v155, v155, 0x3e0293ee, v194
	v_fmamk_f32 v156, v156, 0x3e0293ee, v194
	v_fmamk_f32 v157, v157, 0x3e0293ee, v194
	v_fmamk_f32 v158, v158, 0x3e0293ee, v194
	v_fmamk_f32 v159, v159, 0x3e0293ee, v194
	v_fmamk_f32 v160, v160, 0x3e0293ee, v194
	v_fmamk_f32 v161, v161, 0x3e0293ee, v194
	v_fmamk_f32 v130, v130, 0x3e0293ee, v194
	v_fmamk_f32 v131, v131, 0x3e0293ee, v194
	v_fmamk_f32 v132, v132, 0x3e0293ee, v194
	v_fmamk_f32 v133, v133, 0x3e0293ee, v194
	v_fmamk_f32 v134, v134, 0x3e0293ee, v194
	v_fmamk_f32 v135, v135, 0x3e0293ee, v194
	v_fmamk_f32 v136, v136, 0x3e0293ee, v194
	v_fmamk_f32 v137, v137, 0x3e0293ee, v194
	v_fmamk_f32 v138, v138, 0x3e0293ee, v194
	v_fmamk_f32 v139, v139, 0x3e0293ee, v194
	v_fmamk_f32 v140, v140, 0x3e0293ee, v194
	v_fmamk_f32 v141, v141, 0x3e0293ee, v194
	v_fmamk_f32 v142, v142, 0x3e0293ee, v194
	v_fmamk_f32 v143, v143, 0x3e0293ee, v194
	v_fmamk_f32 v144, v144, 0x3e0293ee, v194
	v_fmac_f32_e32 v194, 0x3e0293ee, v145
	v_exp_f32_e32 v145, v146
	v_exp_f32_e32 v195, v147
	v_exp_f32_e32 v148, v148
	v_exp_f32_e32 v149, v149
	v_exp_f32_e32 v150, v150
	v_exp_f32_e32 v196, v130
	v_add_f32_e32 v130, 0, v145
	v_exp_f32_e32 v151, v151
	v_add_f32_e32 v130, v195, v130
	v_exp_f32_e32 v152, v152
	v_add_f32_e32 v130, v148, v130
	v_exp_f32_e32 v153, v153
	v_add_f32_e32 v130, v149, v130
	v_exp_f32_e32 v154, v154
	v_add_f32_e32 v130, v150, v130
	v_exp_f32_e32 v155, v155
	v_add_f32_e32 v130, v151, v130
	v_exp_f32_e32 v156, v156
	v_add_f32_e32 v130, v152, v130
	v_exp_f32_e32 v157, v157
	v_add_f32_e32 v130, v153, v130
	v_exp_f32_e32 v158, v158
	v_add_f32_e32 v130, v154, v130
	v_exp_f32_e32 v159, v159
	v_add_f32_e32 v130, v155, v130
	v_exp_f32_e32 v160, v160
	v_add_f32_e32 v130, v156, v130
	v_exp_f32_e32 v161, v161
	v_add_f32_e32 v130, v157, v130
	v_add_f32_e32 v130, v158, v130
	v_exp_f32_e32 v197, v131
	v_add_f32_e32 v130, v159, v130
	v_exp_f32_e32 v198, v132
	v_add_f32_e32 v130, v160, v130
	v_exp_f32_e32 v199, v133
	v_add_f32_e32 v130, v161, v130
	v_exp_f32_e32 v200, v134
	v_add_f32_e32 v130, v196, v130
	v_exp_f32_e32 v201, v135
	v_add_f32_e32 v130, v197, v130
	v_exp_f32_e32 v202, v136
	v_add_f32_e32 v130, v198, v130
	v_exp_f32_e32 v203, v137
	v_add_f32_e32 v130, v199, v130
	v_exp_f32_e32 v204, v138
	v_add_f32_e32 v130, v200, v130
	v_exp_f32_e32 v205, v139
	v_add_f32_e32 v130, v201, v130
	v_exp_f32_e32 v206, v140
	v_add_f32_e32 v130, v202, v130
	v_exp_f32_e32 v207, v141
	v_add_f32_e32 v130, v203, v130
	v_exp_f32_e32 v208, v142
	v_add_f32_e32 v130, v204, v130
	v_exp_f32_e32 v209, v143
	v_add_f32_e32 v130, v205, v130
	v_exp_f32_e32 v251, v144
	v_add_f32_e32 v130, v206, v130
	v_exp_f32_e32 v194, v194
	v_add_f32_e32 v130, v207, v130
	v_add_f32_e32 v130, v208, v130
	v_add_f32_e32 v130, v209, v130
	v_add_f32_e32 v130, v251, v130
	v_add_f32_e32 v146, v194, v130
	v_mov_b32_e32 v147, v146
	s_nop 1
	v_permlane32_swap_b32_e32 v146, v147
	v_cvt_pk_bf16_f32 v130, v145, v195
	v_cvt_pk_bf16_f32 v131, v148, v149
	v_cvt_pk_bf16_f32 v132, v150, v151
	v_cvt_pk_bf16_f32 v133, v152, v153
	v_cvt_pk_bf16_f32 v134, v154, v155
	v_cvt_pk_bf16_f32 v135, v156, v157
	v_cvt_pk_bf16_f32 v136, v158, v159
	v_cvt_pk_bf16_f32 v137, v160, v161
	v_cvt_pk_bf16_f32 v138, v196, v197
	v_cvt_pk_bf16_f32 v139, v198, v199
	v_cvt_pk_bf16_f32 v140, v200, v201
	v_cvt_pk_bf16_f32 v141, v202, v203
	v_cvt_pk_bf16_f32 v142, v204, v205
	v_cvt_pk_bf16_f32 v143, v206, v207
	v_cvt_pk_bf16_f32 v144, v208, v209
	v_cvt_pk_bf16_f32 v145, v251, v194
	s_nop 0
	v_permlane32_swap_b32_e32 v130, v132
	v_permlane32_swap_b32_e32 v131, v133
	v_permlane32_swap_b32_e32 v134, v136
	v_permlane32_swap_b32_e32 v135, v137
	v_permlane32_swap_b32_e32 v138, v140
	v_permlane32_swap_b32_e32 v139, v141
	v_permlane32_swap_b32_e32 v142, v144
	v_permlane32_swap_b32_e32 v143, v145
	ds_read_b64_tr_b16 v[148:149], v235 offset:0
	ds_read_b64_tr_b16 v[150:151], v235 offset:0x800
	ds_read_b64_tr_b16 v[152:153], v235 offset:0x1000
	ds_read_b64_tr_b16 v[154:155], v235 offset:0x1800
	ds_read_b64_tr_b16 v[156:157], v235 offset:0x2000
	ds_read_b64_tr_b16 v[158:159], v235 offset:0x2800
	ds_read_b64_tr_b16 v[194:195], v235 offset:0x3000
	ds_read_b64_tr_b16 v[196:197], v235 offset:0x3800
	s_nop 0
	s_waitcnt lgkmcnt(6)
	v_mfma_f32_32x32x16_bf16 v[2:17], v[130:133], v[148:151], v[2:17]
	ds_read_b64_tr_b16 v[148:149], v235 offset:0x200
	ds_read_b64_tr_b16 v[150:151], v235 offset:0xa00
	s_waitcnt lgkmcnt(6)
	v_mfma_f32_32x32x16_bf16 v[2:17], v[134:137], v[152:155], v[2:17]
	ds_read_b64_tr_b16 v[152:153], v235 offset:0x1200
	ds_read_b64_tr_b16 v[154:155], v235 offset:0x1a00
	s_waitcnt lgkmcnt(6)
	v_mfma_f32_32x32x16_bf16 v[2:17], v[138:141], v[156:159], v[2:17]
	ds_read_b64_tr_b16 v[156:157], v235 offset:0x2200
	ds_read_b64_tr_b16 v[158:159], v235 offset:0x2a00
	s_waitcnt lgkmcnt(6)
	v_mfma_f32_32x32x16_bf16 v[2:17], v[142:145], v[194:197], v[2:17]
	ds_read_b64_tr_b16 v[194:195], v235 offset:0x3200
	ds_read_b64_tr_b16 v[196:197], v235 offset:0x3a00
	s_waitcnt lgkmcnt(6)
	v_mfma_f32_32x32x16_bf16 v[18:33], v[130:133], v[148:151], v[18:33]
	ds_read_b64_tr_b16 v[148:149], v235 offset:0x400
	ds_read_b64_tr_b16 v[150:151], v235 offset:0xc00
	s_waitcnt lgkmcnt(6)
	v_mfma_f32_32x32x16_bf16 v[18:33], v[134:137], v[152:155], v[18:33]
	ds_read_b64_tr_b16 v[152:153], v235 offset:0x1400
	ds_read_b64_tr_b16 v[154:155], v235 offset:0x1c00
	s_waitcnt lgkmcnt(6)
	v_mfma_f32_32x32x16_bf16 v[18:33], v[138:141], v[156:159], v[18:33]
	ds_read_b64_tr_b16 v[156:157], v235 offset:0x2400
	ds_read_b64_tr_b16 v[158:159], v235 offset:0x2c00
	s_waitcnt lgkmcnt(6)
	v_mfma_f32_32x32x16_bf16 v[18:33], v[142:145], v[194:197], v[18:33]
	ds_read_b64_tr_b16 v[194:195], v235 offset:0x3400
	ds_read_b64_tr_b16 v[196:197], v235 offset:0x3c00
	s_waitcnt lgkmcnt(6)
	v_mfma_f32_32x32x16_bf16 v[34:49], v[130:133], v[148:151], v[34:49]
	ds_read_b64_tr_b16 v[148:149], v235 offset:0x600
	ds_read_b64_tr_b16 v[150:151], v235 offset:0xe00
	s_waitcnt lgkmcnt(6)
	v_mfma_f32_32x32x16_bf16 v[34:49], v[134:137], v[152:155], v[34:49]
	ds_read_b64_tr_b16 v[152:153], v235 offset:0x1600
	ds_read_b64_tr_b16 v[154:155], v235 offset:0x1e00
	s_waitcnt lgkmcnt(6)
	v_mfma_f32_32x32x16_bf16 v[34:49], v[138:141], v[156:159], v[34:49]
	ds_read_b64_tr_b16 v[156:157], v235 offset:0x2600
	ds_read_b64_tr_b16 v[158:159], v235 offset:0x2e00
	s_waitcnt lgkmcnt(6)
	v_mfma_f32_32x32x16_bf16 v[34:49], v[142:145], v[194:197], v[34:49]
	ds_read_b64_tr_b16 v[194:195], v235 offset:0x3600
	ds_read_b64_tr_b16 v[196:197], v235 offset:0x3e00
	s_waitcnt lgkmcnt(6)
	v_mfma_f32_32x32x16_bf16 v[50:65], v[130:133], v[148:151], v[50:65]
	ds_read_b64_tr_b16 v[148:149], v236 offset:0
	ds_read_b64_tr_b16 v[150:151], v236 offset:0x800
	s_waitcnt lgkmcnt(6)
	v_mfma_f32_32x32x16_bf16 v[50:65], v[134:137], v[152:155], v[50:65]
	ds_read_b64_tr_b16 v[152:153], v236 offset:0x1000
	ds_read_b64_tr_b16 v[154:155], v236 offset:0x1800
	s_waitcnt lgkmcnt(6)
	v_mfma_f32_32x32x16_bf16 v[50:65], v[138:141], v[156:159], v[50:65]
	ds_read_b64_tr_b16 v[156:157], v236 offset:0x2000
	ds_read_b64_tr_b16 v[158:159], v236 offset:0x2800
	s_waitcnt lgkmcnt(6)
	v_mfma_f32_32x32x16_bf16 v[50:65], v[142:145], v[194:197], v[50:65]
	ds_read_b64_tr_b16 v[194:195], v236 offset:0x3000
	ds_read_b64_tr_b16 v[196:197], v236 offset:0x3800
	s_waitcnt lgkmcnt(6)
	v_mfma_f32_32x32x16_bf16 v[66:81], v[130:133], v[148:151], v[66:81]
	ds_read_b64_tr_b16 v[148:149], v236 offset:0x200
	ds_read_b64_tr_b16 v[150:151], v236 offset:0xa00
	s_waitcnt lgkmcnt(6)
	v_mfma_f32_32x32x16_bf16 v[66:81], v[134:137], v[152:155], v[66:81]
	ds_read_b64_tr_b16 v[152:153], v236 offset:0x1200
	ds_read_b64_tr_b16 v[154:155], v236 offset:0x1a00
	s_waitcnt lgkmcnt(6)
	v_mfma_f32_32x32x16_bf16 v[66:81], v[138:141], v[156:159], v[66:81]
	ds_read_b64_tr_b16 v[156:157], v236 offset:0x2200
	ds_read_b64_tr_b16 v[158:159], v236 offset:0x2a00
	s_waitcnt lgkmcnt(6)
	v_mfma_f32_32x32x16_bf16 v[66:81], v[142:145], v[194:197], v[66:81]
	ds_read_b64_tr_b16 v[194:195], v236 offset:0x3200
	ds_read_b64_tr_b16 v[196:197], v236 offset:0x3a00
	s_waitcnt lgkmcnt(6)
	v_mfma_f32_32x32x16_bf16 v[82:97], v[130:133], v[148:151], v[82:97]
	ds_read_b64_tr_b16 v[148:149], v236 offset:0x400
	ds_read_b64_tr_b16 v[150:151], v236 offset:0xc00
	s_waitcnt lgkmcnt(6)
	v_mfma_f32_32x32x16_bf16 v[82:97], v[134:137], v[152:155], v[82:97]
	ds_read_b64_tr_b16 v[152:153], v236 offset:0x1400
	ds_read_b64_tr_b16 v[154:155], v236 offset:0x1c00
	s_waitcnt lgkmcnt(6)
	v_mfma_f32_32x32x16_bf16 v[82:97], v[138:141], v[156:159], v[82:97]
	ds_read_b64_tr_b16 v[156:157], v236 offset:0x2400
	ds_read_b64_tr_b16 v[158:159], v236 offset:0x2c00
	s_waitcnt lgkmcnt(6)
	v_mfma_f32_32x32x16_bf16 v[82:97], v[142:145], v[194:197], v[82:97]
	ds_read_b64_tr_b16 v[194:195], v236 offset:0x3400
	ds_read_b64_tr_b16 v[196:197], v236 offset:0x3c00
	s_waitcnt lgkmcnt(6)
	v_mfma_f32_32x32x16_bf16 v[98:113], v[130:133], v[148:151], v[98:113]
	ds_read_b64_tr_b16 v[148:149], v236 offset:0x600
	ds_read_b64_tr_b16 v[150:151], v236 offset:0xe00
	s_waitcnt lgkmcnt(6)
	v_mfma_f32_32x32x16_bf16 v[98:113], v[134:137], v[152:155], v[98:113]
	ds_read_b64_tr_b16 v[152:153], v236 offset:0x1600
	ds_read_b64_tr_b16 v[154:155], v236 offset:0x1e00
	s_waitcnt lgkmcnt(6)
	v_mfma_f32_32x32x16_bf16 v[98:113], v[138:141], v[156:159], v[98:113]
	ds_read_b64_tr_b16 v[156:157], v236 offset:0x2600
	ds_read_b64_tr_b16 v[158:159], v236 offset:0x2e00
	s_waitcnt lgkmcnt(6)
	v_mfma_f32_32x32x16_bf16 v[98:113], v[142:145], v[194:197], v[98:113]
	ds_read_b64_tr_b16 v[194:195], v236 offset:0x3600
	ds_read_b64_tr_b16 v[196:197], v236 offset:0x3e00
	s_waitcnt lgkmcnt(6)
	v_mfma_f32_32x32x16_bf16 v[114:129], v[130:133], v[148:151], v[114:129]
	s_waitcnt lgkmcnt(4)
	v_mfma_f32_32x32x16_bf16 v[114:129], v[134:137], v[152:155], v[114:129]
	s_waitcnt lgkmcnt(2)
	v_mfma_f32_32x32x16_bf16 v[114:129], v[138:141], v[156:159], v[114:129]
	s_waitcnt lgkmcnt(0)
	v_mfma_f32_32x32x16_bf16 v[114:129], v[142:145], v[194:197], v[114:129]
	s_mov_b64 s[80:81], 0xc0100
	s_mov_b64 s[82:83], 0xe0100
	s_branch .LBB0_584
.LBB0_603:
	s_barrier
	s_and_saveexec_b64 s[0:1], s[4:5]
	s_cbranch_execz .LBB0_556
	ds_write_b32 v225, v237
	s_branch .LBB0_556

.LBB0_929:
	s_add_u32 s79, s30, s84
	s_addc_u32 s90, s31, s85
	s_and_b64 s[86:87], s[0:1], exec
	s_cselect_b32 s94, s38, s79
	s_cselect_b32 s95, s39, s90
	s_add_u32 s86, s94, 0x8000
	s_addc_u32 s87, s95, 0
	s_add_i32 s79, 0, 0x10000
	s_and_b64 s[0:1], s[0:1], exec
	s_cselect_b32 s91, s41, s51
	s_cselect_b32 s90, s40, s43
	s_add_i32 vcc_lo, 0, 0x14000
	v_add_u32_e32 v148, s79, v205
	v_add_u32_e32 v156, vcc_lo, v205
	ds_read_b128 v[136:139], v148
	ds_read_b128 v[140:143], v148 offset:1024
	ds_read_b128 v[144:147], v148 offset:2048
	ds_read_b128 v[148:151], v148 offset:3072
	ds_read_b128 v[152:155], v156
	ds_read_b128 v[168:171], v156 offset:1024
	ds_read_b128 v[172:175], v156 offset:2048
	ds_read_b128 v[176:179], v156 offset:3072
	v_lshl_add_u64 v[156:157], s[30:31], 0, v[134:135]
	s_add_i32 m0, s72, 0xc000
	ds_read_b128 v[180:183], v222
	ds_read_b128 v[184:187], v222 offset:1024
	ds_read_b128 v[188:191], v222 offset:2048
	ds_read_b128 v[192:195], v222 offset:3072
	ds_read_b128 v[196:199], v222 offset:4096
	ds_read_b128 v[234:237], v222 offset:5120
	ds_read_b128 v[238:241], v222 offset:6144
	ds_read_b128 v[242:245], v222 offset:7168
	global_load_lds_dwordx4 v[156:157], off
	v_lshl_add_u64 v[156:157], s[30:31], 0, v[132:133]
	s_add_i32 m0, s72, 0xe000
	s_nop 0
	global_load_lds_dwordx4 v[156:157], off
	s_waitcnt vmcnt(8)
	s_waitcnt lgkmcnt(0)
	s_barrier
	s_setprio 1
	s_waitcnt lgkmcnt(0)
	v_mfma_f32_16x16x32_bf16 v[6:9], v[136:139], v[180:183], v[6:9]
	v_mfma_f32_16x16x32_bf16 v[126:129], v[144:147], v[180:183], v[126:129]
	v_mfma_f32_16x16x32_bf16 v[122:125], v[136:139], v[188:191], v[122:125]
	v_mfma_f32_16x16x32_bf16 v[118:121], v[144:147], v[188:191], v[118:121]
	v_mfma_f32_16x16x32_bf16 v[114:117], v[136:139], v[196:199], v[114:117]
	v_mfma_f32_16x16x32_bf16 v[110:113], v[144:147], v[196:199], v[110:113]
	v_mfma_f32_16x16x32_bf16 v[106:109], v[136:139], v[238:241], v[106:109]
	v_mfma_f32_16x16x32_bf16 v[102:105], v[144:147], v[238:241], v[102:105]
	v_mfma_f32_16x16x32_bf16 v[6:9], v[140:143], v[184:187], v[6:9]
	v_mfma_f32_16x16x32_bf16 v[126:129], v[148:151], v[184:187], v[126:129]
	v_mfma_f32_16x16x32_bf16 v[122:125], v[140:143], v[192:195], v[122:125]
	v_mfma_f32_16x16x32_bf16 v[118:121], v[148:151], v[192:195], v[118:121]
	v_mfma_f32_16x16x32_bf16 v[114:117], v[140:143], v[234:237], v[114:117]
	v_mfma_f32_16x16x32_bf16 v[110:113], v[148:151], v[234:237], v[110:113]
	v_mfma_f32_16x16x32_bf16 v[106:109], v[140:143], v[242:245], v[106:109]
	v_mfma_f32_16x16x32_bf16 v[102:105], v[148:151], v[242:245], v[102:105]
	s_setprio 0
	s_setprio 1
	v_mfma_f32_16x16x32_bf16 v[98:101], v[152:155], v[180:183], v[98:101]
	v_mfma_f32_16x16x32_bf16 v[94:97], v[172:175], v[180:183], v[94:97]
	v_mfma_f32_16x16x32_bf16 v[90:93], v[152:155], v[188:191], v[90:93]
	v_mfma_f32_16x16x32_bf16 v[86:89], v[172:175], v[188:191], v[86:89]
	v_mfma_f32_16x16x32_bf16 v[82:85], v[152:155], v[196:199], v[82:85]
	v_mfma_f32_16x16x32_bf16 v[78:81], v[172:175], v[196:199], v[78:81]
	v_mfma_f32_16x16x32_bf16 v[74:77], v[152:155], v[238:241], v[74:77]
	v_mfma_f32_16x16x32_bf16 v[70:73], v[172:175], v[238:241], v[70:73]
	v_mfma_f32_16x16x32_bf16 v[98:101], v[168:171], v[184:187], v[98:101]
	v_mfma_f32_16x16x32_bf16 v[94:97], v[176:179], v[184:187], v[94:97]
	v_mfma_f32_16x16x32_bf16 v[90:93], v[168:171], v[192:195], v[90:93]
	v_mfma_f32_16x16x32_bf16 v[86:89], v[176:179], v[192:195], v[86:89]
	v_mfma_f32_16x16x32_bf16 v[82:85], v[168:171], v[234:237], v[82:85]
	v_mfma_f32_16x16x32_bf16 v[78:81], v[176:179], v[234:237], v[78:81]
	v_mfma_f32_16x16x32_bf16 v[74:77], v[168:171], v[242:245], v[74:77]
	v_mfma_f32_16x16x32_bf16 v[70:73], v[176:179], v[242:245], v[70:73]
	s_setprio 0
	s_barrier
	s_add_i32 s0, s79, s44
	v_lshl_add_u64 v[156:157], s[90:91], 0, v[210:211]
	s_mov_b32 m0, s0
	ds_read_b128 v[180:183], v222 offset:16384
	ds_read_b128 v[184:187], v222 offset:17408
	ds_read_b128 v[188:191], v222 offset:18432
	ds_read_b128 v[192:195], v222 offset:19456
	ds_read_b128 v[196:199], v222 offset:20480
	ds_read_b128 v[234:237], v222 offset:21504
	ds_read_b128 v[238:241], v222 offset:22528
	ds_read_b128 v[242:245], v222 offset:23552
	global_load_lds_dwordx4 v[156:157], off
	s_add_i32 m0, s0, 0x2000
	s_add_u32 s0, s90, 0x160000
	v_lshl_add_u64 v[200:201], s[90:91], 0, v[162:163]
	s_addc_u32 s1, s91, 0
	s_add_i32 s79, vcc_lo, s44
	global_load_lds_dwordx4 v[200:201], off
	v_lshl_add_u64 v[224:225], s[0:1], 0, v[210:211]
	s_mov_b32 m0, s79
	s_nop 0
	global_load_lds_dwordx4 v[224:225], off
	v_lshl_add_u64 v[224:225], s[0:1], 0, v[162:163]
	s_add_i32 m0, s79, 0x2000
	s_nop 0
	global_load_lds_dwordx4 v[224:225], off
	s_waitcnt vmcnt(6)
	s_waitcnt lgkmcnt(0)
	s_barrier
	s_setprio 1
	s_waitcnt lgkmcnt(0)
	v_mfma_f32_16x16x32_bf16 v[66:69], v[136:139], v[180:183], v[66:69]
	v_mfma_f32_16x16x32_bf16 v[62:65], v[144:147], v[180:183], v[62:65]
	v_mfma_f32_16x16x32_bf16 v[58:61], v[136:139], v[188:191], v[58:61]
	v_mfma_f32_16x16x32_bf16 v[54:57], v[144:147], v[188:191], v[54:57]
	v_mfma_f32_16x16x32_bf16 v[50:53], v[136:139], v[196:199], v[50:53]
	v_mfma_f32_16x16x32_bf16 v[46:49], v[144:147], v[196:199], v[46:49]
	v_mfma_f32_16x16x32_bf16 v[42:45], v[136:139], v[238:241], v[42:45]
	v_mfma_f32_16x16x32_bf16 v[38:41], v[144:147], v[238:241], v[38:41]
	v_mfma_f32_16x16x32_bf16 v[66:69], v[140:143], v[184:187], v[66:69]
	v_mfma_f32_16x16x32_bf16 v[62:65], v[148:151], v[184:187], v[62:65]
	v_mfma_f32_16x16x32_bf16 v[58:61], v[140:143], v[192:195], v[58:61]
	v_mfma_f32_16x16x32_bf16 v[54:57], v[148:151], v[192:195], v[54:57]
	v_mfma_f32_16x16x32_bf16 v[50:53], v[140:143], v[234:237], v[50:53]
	v_mfma_f32_16x16x32_bf16 v[46:49], v[148:151], v[234:237], v[46:49]
	v_mfma_f32_16x16x32_bf16 v[42:45], v[140:143], v[242:245], v[42:45]
	v_mfma_f32_16x16x32_bf16 v[38:41], v[148:151], v[242:245], v[38:41]
	s_setprio 0
	s_setprio 1
	v_mfma_f32_16x16x32_bf16 v[34:37], v[152:155], v[180:183], v[34:37]
	v_mfma_f32_16x16x32_bf16 v[30:33], v[172:175], v[180:183], v[30:33]
	v_mfma_f32_16x16x32_bf16 v[26:29], v[152:155], v[188:191], v[26:29]
	v_mfma_f32_16x16x32_bf16 v[22:25], v[172:175], v[188:191], v[22:25]
	v_mfma_f32_16x16x32_bf16 v[18:21], v[152:155], v[196:199], v[18:21]
	v_mfma_f32_16x16x32_bf16 v[14:17], v[172:175], v[196:199], v[14:17]
	v_mfma_f32_16x16x32_bf16 v[10:13], v[152:155], v[238:241], v[10:13]
	v_mfma_f32_16x16x32_bf16 v[2:5], v[172:175], v[238:241], v[2:5]
	v_mfma_f32_16x16x32_bf16 v[34:37], v[168:171], v[184:187], v[34:37]
	v_mfma_f32_16x16x32_bf16 v[30:33], v[176:179], v[184:187], v[30:33]
	v_mfma_f32_16x16x32_bf16 v[26:29], v[168:171], v[192:195], v[26:29]
	v_mfma_f32_16x16x32_bf16 v[22:25], v[176:179], v[192:195], v[22:25]
	v_mfma_f32_16x16x32_bf16 v[18:21], v[168:171], v[234:237], v[18:21]
	v_mfma_f32_16x16x32_bf16 v[14:17], v[176:179], v[234:237], v[14:17]
	v_mfma_f32_16x16x32_bf16 v[10:13], v[168:171], v[242:245], v[10:13]
	v_mfma_f32_16x16x32_bf16 v[2:5], v[176:179], v[242:245], v[2:5]
	s_setprio 0
	s_barrier
	s_add_i32 s79, 0, 0x18000
	s_add_i32 vcc_lo, 0, 0x1c000
	v_add_u32_e32 v148, s79, v205
	v_add_u32_e32 v176, vcc_lo, v205
	ds_read_b128 v[136:139], v148
	ds_read_b128 v[140:143], v148 offset:1024
	ds_read_b128 v[144:147], v148 offset:2048
	ds_read_b128 v[148:151], v148 offset:3072
	ds_read_b128 v[152:155], v176
	ds_read_b128 v[168:171], v176 offset:1024
	ds_read_b128 v[172:175], v176 offset:2048
	ds_read_b128 v[176:179], v176 offset:3072
	s_add_u32 s0, s94, 0x4000
	s_addc_u32 s1, s95, 0
	s_mov_b32 m0, s22
	v_lshl_add_u64 v[224:225], s[0:1], 0, v[158:159]
	ds_read_b128 v[180:183], v222 offset:32768
	ds_read_b128 v[184:187], v222 offset:33792
	ds_read_b128 v[188:191], v222 offset:34816
	ds_read_b128 v[192:195], v222 offset:35840
	ds_read_b128 v[196:199], v222 offset:36864
	ds_read_b128 v[234:237], v222 offset:37888
	ds_read_b128 v[238:241], v222 offset:38912
	ds_read_b128 v[242:245], v222 offset:39936
	global_load_lds_dwordx4 v[224:225], off
	v_lshl_add_u64 v[224:225], s[0:1], 0, v[160:161]
	s_mov_b32 m0, s5
	s_nop 0
	global_load_lds_dwordx4 v[224:225], off
	v_lshl_add_u64 v[224:225], s[94:95], 0, v[158:159]
	s_mov_b32 m0, s72
	s_nop 0
	global_load_lds_dwordx4 v[224:225], off
	v_lshl_add_u64 v[224:225], s[94:95], 0, v[160:161]
	s_mov_b32 m0, s73
	s_nop 0
	global_load_lds_dwordx4 v[224:225], off
	s_waitcnt vmcnt(8)
	s_waitcnt lgkmcnt(0)
	s_barrier
	s_setprio 1
	s_waitcnt lgkmcnt(0)
	v_mfma_f32_16x16x32_bf16 v[6:9], v[136:139], v[180:183], v[6:9]
	v_mfma_f32_16x16x32_bf16 v[126:129], v[144:147], v[180:183], v[126:129]
	v_mfma_f32_16x16x32_bf16 v[122:125], v[136:139], v[188:191], v[122:125]
	v_mfma_f32_16x16x32_bf16 v[118:121], v[144:147], v[188:191], v[118:121]
	v_mfma_f32_16x16x32_bf16 v[114:117], v[136:139], v[196:199], v[114:117]
	v_mfma_f32_16x16x32_bf16 v[110:113], v[144:147], v[196:199], v[110:113]
	v_mfma_f32_16x16x32_bf16 v[106:109], v[136:139], v[238:241], v[106:109]
	v_mfma_f32_16x16x32_bf16 v[102:105], v[144:147], v[238:241], v[102:105]
	v_mfma_f32_16x16x32_bf16 v[6:9], v[140:143], v[184:187], v[6:9]
	v_mfma_f32_16x16x32_bf16 v[126:129], v[148:151], v[184:187], v[126:129]
	v_mfma_f32_16x16x32_bf16 v[122:125], v[140:143], v[192:195], v[122:125]
	v_mfma_f32_16x16x32_bf16 v[118:121], v[148:151], v[192:195], v[118:121]
	v_mfma_f32_16x16x32_bf16 v[114:117], v[140:143], v[234:237], v[114:117]
	v_mfma_f32_16x16x32_bf16 v[110:113], v[148:151], v[234:237], v[110:113]
	v_mfma_f32_16x16x32_bf16 v[106:109], v[140:143], v[242:245], v[106:109]
	v_mfma_f32_16x16x32_bf16 v[102:105], v[148:151], v[242:245], v[102:105]
	s_setprio 0
	s_setprio 1
	v_mfma_f32_16x16x32_bf16 v[98:101], v[152:155], v[180:183], v[98:101]
	v_mfma_f32_16x16x32_bf16 v[94:97], v[172:175], v[180:183], v[94:97]
	v_mfma_f32_16x16x32_bf16 v[90:93], v[152:155], v[188:191], v[90:93]
	v_mfma_f32_16x16x32_bf16 v[86:89], v[172:175], v[188:191], v[86:89]
	v_mfma_f32_16x16x32_bf16 v[82:85], v[152:155], v[196:199], v[82:85]
	v_mfma_f32_16x16x32_bf16 v[78:81], v[172:175], v[196:199], v[78:81]
	v_mfma_f32_16x16x32_bf16 v[74:77], v[152:155], v[238:241], v[74:77]
	v_mfma_f32_16x16x32_bf16 v[70:73], v[172:175], v[238:241], v[70:73]
	v_mfma_f32_16x16x32_bf16 v[98:101], v[168:171], v[184:187], v[98:101]
	v_mfma_f32_16x16x32_bf16 v[94:97], v[176:179], v[184:187], v[94:97]
	v_mfma_f32_16x16x32_bf16 v[90:93], v[168:171], v[192:195], v[90:93]
	v_mfma_f32_16x16x32_bf16 v[86:89], v[176:179], v[192:195], v[86:89]
	v_mfma_f32_16x16x32_bf16 v[82:85], v[168:171], v[234:237], v[82:85]
	v_mfma_f32_16x16x32_bf16 v[78:81], v[176:179], v[234:237], v[78:81]
	v_mfma_f32_16x16x32_bf16 v[74:77], v[168:171], v[242:245], v[74:77]
	v_mfma_f32_16x16x32_bf16 v[70:73], v[176:179], v[242:245], v[70:73]
	s_setprio 0
	s_barrier
	s_add_i32 s0, s79, s44
	v_lshl_add_u64 v[156:157], v[156:157], 0, s[48:49]
	s_mov_b32 m0, s0
	ds_read_b128 v[180:183], v222 offset:49152
	ds_read_b128 v[184:187], v222 offset:50176
	ds_read_b128 v[188:191], v222 offset:51200
	ds_read_b128 v[192:195], v222 offset:52224
	ds_read_b128 v[196:199], v222 offset:53248
	ds_read_b128 v[234:237], v222 offset:54272
	ds_read_b128 v[238:241], v222 offset:55296
	ds_read_b128 v[242:245], v222 offset:56320
	global_load_lds_dwordx4 v[156:157], off
	s_add_i32 m0, s0, 0x2000
	s_add_u32 s0, s90, 0x160080
	v_lshl_add_u64 v[156:157], v[200:201], 0, s[48:49]
	s_addc_u32 s1, s91, 0
	s_add_i32 s79, vcc_lo, s44
	global_load_lds_dwordx4 v[156:157], off
	v_lshl_add_u64 v[156:157], s[0:1], 0, v[210:211]
	s_mov_b32 m0, s79
	s_nop 0
	global_load_lds_dwordx4 v[156:157], off
	v_lshl_add_u64 v[156:157], s[0:1], 0, v[162:163]
	s_add_i32 m0, s79, 0x2000
	s_nop 0
	global_load_lds_dwordx4 v[156:157], off
	v_lshl_add_u64 v[156:157], s[86:87], 0, v[158:159]
	s_mov_b32 m0, s23
	s_nop 0
	global_load_lds_dwordx4 v[156:157], off
	v_lshl_add_u64 v[156:157], s[86:87], 0, v[160:161]
	s_mov_b32 m0, s65
	s_nop 0
	global_load_lds_dwordx4 v[156:157], off
	s_waitcnt vmcnt(6)
	s_waitcnt lgkmcnt(0)
	s_barrier
	s_setprio 1
	s_waitcnt lgkmcnt(0)
	v_mfma_f32_16x16x32_bf16 v[66:69], v[136:139], v[180:183], v[66:69]
	v_mfma_f32_16x16x32_bf16 v[62:65], v[144:147], v[180:183], v[62:65]
	v_mfma_f32_16x16x32_bf16 v[58:61], v[136:139], v[188:191], v[58:61]
	v_mfma_f32_16x16x32_bf16 v[54:57], v[144:147], v[188:191], v[54:57]
	v_mfma_f32_16x16x32_bf16 v[50:53], v[136:139], v[196:199], v[50:53]
	v_mfma_f32_16x16x32_bf16 v[46:49], v[144:147], v[196:199], v[46:49]
	v_mfma_f32_16x16x32_bf16 v[42:45], v[136:139], v[238:241], v[42:45]
	v_mfma_f32_16x16x32_bf16 v[38:41], v[144:147], v[238:241], v[38:41]
	v_mfma_f32_16x16x32_bf16 v[66:69], v[140:143], v[184:187], v[66:69]
	v_mfma_f32_16x16x32_bf16 v[62:65], v[148:151], v[184:187], v[62:65]
	v_mfma_f32_16x16x32_bf16 v[58:61], v[140:143], v[192:195], v[58:61]
	v_mfma_f32_16x16x32_bf16 v[54:57], v[148:151], v[192:195], v[54:57]
	v_mfma_f32_16x16x32_bf16 v[50:53], v[140:143], v[234:237], v[50:53]
	v_mfma_f32_16x16x32_bf16 v[46:49], v[148:151], v[234:237], v[46:49]
	v_mfma_f32_16x16x32_bf16 v[42:45], v[140:143], v[242:245], v[42:45]
	v_mfma_f32_16x16x32_bf16 v[38:41], v[148:151], v[242:245], v[38:41]
	s_setprio 0
	s_setprio 1
	v_mfma_f32_16x16x32_bf16 v[34:37], v[152:155], v[180:183], v[34:37]
	v_mfma_f32_16x16x32_bf16 v[30:33], v[172:175], v[180:183], v[30:33]
	v_mfma_f32_16x16x32_bf16 v[26:29], v[152:155], v[188:191], v[26:29]
	v_mfma_f32_16x16x32_bf16 v[22:25], v[172:175], v[188:191], v[22:25]
	v_mfma_f32_16x16x32_bf16 v[18:21], v[152:155], v[196:199], v[18:21]
	v_mfma_f32_16x16x32_bf16 v[14:17], v[172:175], v[196:199], v[14:17]
	v_mfma_f32_16x16x32_bf16 v[10:13], v[152:155], v[238:241], v[10:13]
	v_mfma_f32_16x16x32_bf16 v[2:5], v[172:175], v[238:241], v[2:5]
	v_mfma_f32_16x16x32_bf16 v[34:37], v[168:171], v[184:187], v[34:37]
	v_mfma_f32_16x16x32_bf16 v[30:33], v[176:179], v[184:187], v[30:33]
	v_mfma_f32_16x16x32_bf16 v[26:29], v[168:171], v[192:195], v[26:29]
	v_mfma_f32_16x16x32_bf16 v[22:25], v[176:179], v[192:195], v[22:25]
	v_mfma_f32_16x16x32_bf16 v[18:21], v[168:171], v[234:237], v[18:21]
	v_mfma_f32_16x16x32_bf16 v[14:17], v[176:179], v[234:237], v[14:17]
	v_mfma_f32_16x16x32_bf16 v[10:13], v[168:171], v[242:245], v[10:13]
	v_mfma_f32_16x16x32_bf16 v[2:5], v[176:179], v[242:245], v[2:5]
	s_setprio 0
	s_barrier
	s_add_i32 s78, s78, 2
	s_add_u32 s84, s84, 0x10000
	s_addc_u32 s85, s85, 0
	s_add_u32 s43, s43, 0x100
	s_addc_u32 s51, s51, 0
	v_lshl_add_u64 v[134:135], v[134:135], 0, s[92:93]
	s_cmpk_gt_u32 s78, 0x55
	v_lshl_add_u64 v[132:133], v[132:133], 0, s[92:93]
	s_cbranch_scc1 .LBB0_936

.LBB0_1015:
	s_add_u32 s0, s14, 0x4000
	s_addc_u32 s1, s15, 0
	s_cmpk_eq_i32 s38, 0x54
	s_cselect_b32 s0, s6, s0
	s_cselect_b32 s1, s7, s1
	s_cselect_b32 s18, s12, s36
	s_cselect_b32 s19, s13, s37
	s_add_u32 s16, s0, 0x8000
	s_addc_u32 s17, s1, 0
	s_add_i32 s39, 0, 0x10000
	s_add_i32 s42, 0, 0x14000
	v_add_u32_e32 v110, s39, v163
	v_add_u32_e32 v160, s42, v163
	ds_read_b128 v[98:101], v110
	ds_read_b128 v[102:105], v110 offset:1024
	ds_read_b128 v[106:109], v110 offset:2048
	ds_read_b128 v[110:113], v110 offset:3072
	ds_read_b128 v[156:159], v160
	ds_read_b128 v[166:169], v160 offset:1024
	ds_read_b128 v[170:173], v160 offset:2048
	ds_read_b128 v[174:177], v160 offset:3072
	v_lshl_add_u64 v[160:161], s[14:15], 0, v[152:153]
	s_add_i32 m0, s22, 0xc000
	ds_read_b128 v[178:181], v165
	ds_read_b128 v[182:185], v165 offset:1024
	ds_read_b128 v[186:189], v165 offset:2048
	ds_read_b128 v[190:193], v165 offset:3072
	ds_read_b128 v[194:197], v165 offset:4096
	ds_read_b128 v[198:201], v165 offset:5120
	ds_read_b128 v[202:205], v165 offset:6144
	ds_read_b128 v[206:209], v165 offset:7168
	global_load_lds_dwordx4 v[160:161], off
	v_lshl_add_u64 v[160:161], s[14:15], 0, v[154:155]
	s_add_i32 m0, s22, 0xe000
	s_nop 0
	global_load_lds_dwordx4 v[160:161], off
	s_waitcnt vmcnt(8)
	s_waitcnt lgkmcnt(0)
	s_barrier
	s_setprio 1
	s_waitcnt lgkmcnt(0)
	v_mfma_f32_16x16x32_bf16 v[142:145], v[98:101], v[178:181], v[142:145]
	v_mfma_f32_16x16x32_bf16 v[138:141], v[106:109], v[178:181], v[138:141]
	v_mfma_f32_16x16x32_bf16 v[126:129], v[98:101], v[186:189], v[126:129]
	v_mfma_f32_16x16x32_bf16 v[122:125], v[106:109], v[186:189], v[122:125]
	v_mfma_f32_16x16x32_bf16 v[94:97], v[98:101], v[194:197], v[94:97]
	v_mfma_f32_16x16x32_bf16 v[90:93], v[106:109], v[194:197], v[90:93]
	v_mfma_f32_16x16x32_bf16 v[78:81], v[98:101], v[202:205], v[78:81]
	v_mfma_f32_16x16x32_bf16 v[74:77], v[106:109], v[202:205], v[74:77]
	v_mfma_f32_16x16x32_bf16 v[142:145], v[102:105], v[182:185], v[142:145]
	v_mfma_f32_16x16x32_bf16 v[138:141], v[110:113], v[182:185], v[138:141]
	v_mfma_f32_16x16x32_bf16 v[126:129], v[102:105], v[190:193], v[126:129]
	v_mfma_f32_16x16x32_bf16 v[122:125], v[110:113], v[190:193], v[122:125]
	v_mfma_f32_16x16x32_bf16 v[94:97], v[102:105], v[198:201], v[94:97]
	v_mfma_f32_16x16x32_bf16 v[90:93], v[110:113], v[198:201], v[90:93]
	v_mfma_f32_16x16x32_bf16 v[78:81], v[102:105], v[206:209], v[78:81]
	v_mfma_f32_16x16x32_bf16 v[74:77], v[110:113], v[206:209], v[74:77]
	s_setprio 0
	s_setprio 1
	v_mfma_f32_16x16x32_bf16 v[134:137], v[156:159], v[178:181], v[134:137]
	v_mfma_f32_16x16x32_bf16 v[130:133], v[170:173], v[178:181], v[130:133]
	v_mfma_f32_16x16x32_bf16 v[118:121], v[156:159], v[186:189], v[118:121]
	v_mfma_f32_16x16x32_bf16 v[114:117], v[170:173], v[186:189], v[114:117]
	v_mfma_f32_16x16x32_bf16 v[86:89], v[156:159], v[194:197], v[86:89]
	v_mfma_f32_16x16x32_bf16 v[82:85], v[170:173], v[194:197], v[82:85]
	v_mfma_f32_16x16x32_bf16 v[70:73], v[156:159], v[202:205], v[70:73]
	v_mfma_f32_16x16x32_bf16 v[66:69], v[170:173], v[202:205], v[66:69]
	v_mfma_f32_16x16x32_bf16 v[134:137], v[166:169], v[182:185], v[134:137]
	v_mfma_f32_16x16x32_bf16 v[130:133], v[174:177], v[182:185], v[130:133]
	v_mfma_f32_16x16x32_bf16 v[118:121], v[166:169], v[190:193], v[118:121]
	v_mfma_f32_16x16x32_bf16 v[114:117], v[174:177], v[190:193], v[114:117]
	v_mfma_f32_16x16x32_bf16 v[86:89], v[166:169], v[198:201], v[86:89]
	v_mfma_f32_16x16x32_bf16 v[82:85], v[174:177], v[198:201], v[82:85]
	v_mfma_f32_16x16x32_bf16 v[70:73], v[166:169], v[206:209], v[70:73]
	v_mfma_f32_16x16x32_bf16 v[66:69], v[174:177], v[206:209], v[66:69]
	s_setprio 0
	s_barrier
	s_add_i32 s39, s39, s20
	v_lshl_add_u64 v[160:161], s[18:19], 0, v[210:211]
	s_mov_b32 m0, s39
	ds_read_b128 v[178:181], v165 offset:16384
	ds_read_b128 v[182:185], v165 offset:17408
	ds_read_b128 v[186:189], v165 offset:18432
	ds_read_b128 v[190:193], v165 offset:19456
	ds_read_b128 v[194:197], v165 offset:20480
	ds_read_b128 v[198:201], v165 offset:21504
	ds_read_b128 v[202:205], v165 offset:22528
	ds_read_b128 v[206:209], v165 offset:23552
	global_load_lds_dwordx4 v[160:161], off
	s_add_i32 m0, s39, 0x2000
	s_add_u32 s40, s18, 0x160000
	v_lshl_add_u64 v[216:217], s[18:19], 0, v[146:147]
	s_addc_u32 s41, s19, 0
	s_add_i32 s39, s42, s20
	global_load_lds_dwordx4 v[216:217], off
	v_lshl_add_u64 v[218:219], s[40:41], 0, v[210:211]
	s_mov_b32 m0, s39
	s_nop 0
	global_load_lds_dwordx4 v[218:219], off
	v_lshl_add_u64 v[218:219], s[40:41], 0, v[146:147]
	s_add_i32 m0, s39, 0x2000
	s_nop 0
	global_load_lds_dwordx4 v[218:219], off
	s_waitcnt vmcnt(6)
	s_waitcnt lgkmcnt(0)
	s_barrier
	s_setprio 1
	s_waitcnt lgkmcnt(0)
	v_mfma_f32_16x16x32_bf16 v[62:65], v[98:101], v[178:181], v[62:65]
	v_mfma_f32_16x16x32_bf16 v[58:61], v[106:109], v[178:181], v[58:61]
	v_mfma_f32_16x16x32_bf16 v[50:53], v[98:101], v[186:189], v[50:53]
	v_mfma_f32_16x16x32_bf16 v[42:45], v[106:109], v[186:189], v[42:45]
	v_mfma_f32_16x16x32_bf16 v[34:37], v[98:101], v[194:197], v[34:37]
	v_mfma_f32_16x16x32_bf16 v[26:29], v[106:109], v[194:197], v[26:29]
	v_mfma_f32_16x16x32_bf16 v[18:21], v[98:101], v[202:205], v[18:21]
	v_mfma_f32_16x16x32_bf16 v[10:13], v[106:109], v[202:205], v[10:13]
	v_mfma_f32_16x16x32_bf16 v[62:65], v[102:105], v[182:185], v[62:65]
	v_mfma_f32_16x16x32_bf16 v[58:61], v[110:113], v[182:185], v[58:61]
	v_mfma_f32_16x16x32_bf16 v[50:53], v[102:105], v[190:193], v[50:53]
	v_mfma_f32_16x16x32_bf16 v[42:45], v[110:113], v[190:193], v[42:45]
	v_mfma_f32_16x16x32_bf16 v[34:37], v[102:105], v[198:201], v[34:37]
	v_mfma_f32_16x16x32_bf16 v[26:29], v[110:113], v[198:201], v[26:29]
	v_mfma_f32_16x16x32_bf16 v[18:21], v[102:105], v[206:209], v[18:21]
	v_mfma_f32_16x16x32_bf16 v[10:13], v[110:113], v[206:209], v[10:13]
	s_setprio 0
	s_setprio 1
	v_mfma_f32_16x16x32_bf16 v[54:57], v[156:159], v[178:181], v[54:57]
	v_mfma_f32_16x16x32_bf16 v[46:49], v[170:173], v[178:181], v[46:49]
	v_mfma_f32_16x16x32_bf16 v[38:41], v[156:159], v[186:189], v[38:41]
	v_mfma_f32_16x16x32_bf16 v[30:33], v[170:173], v[186:189], v[30:33]
	v_mfma_f32_16x16x32_bf16 v[22:25], v[156:159], v[194:197], v[22:25]
	v_mfma_f32_16x16x32_bf16 v[14:17], v[170:173], v[194:197], v[14:17]
	v_mfma_f32_16x16x32_bf16 v[6:9], v[156:159], v[202:205], v[6:9]
	v_mfma_f32_16x16x32_bf16 v[2:5], v[170:173], v[202:205], v[2:5]
	v_mfma_f32_16x16x32_bf16 v[54:57], v[166:169], v[182:185], v[54:57]
	v_mfma_f32_16x16x32_bf16 v[46:49], v[174:177], v[182:185], v[46:49]
	v_mfma_f32_16x16x32_bf16 v[38:41], v[166:169], v[190:193], v[38:41]
	v_mfma_f32_16x16x32_bf16 v[30:33], v[174:177], v[190:193], v[30:33]
	v_mfma_f32_16x16x32_bf16 v[22:25], v[166:169], v[198:201], v[22:25]
	v_mfma_f32_16x16x32_bf16 v[14:17], v[174:177], v[198:201], v[14:17]
	v_mfma_f32_16x16x32_bf16 v[6:9], v[166:169], v[206:209], v[6:9]
	v_mfma_f32_16x16x32_bf16 v[2:5], v[174:177], v[206:209], v[2:5]
	s_setprio 0
	s_barrier
	s_add_i32 s39, 0, 0x18000
	s_add_i32 s40, 0, 0x1c000
	v_add_u32_e32 v110, s39, v163
	v_add_u32_e32 v174, s40, v163
	ds_read_b128 v[98:101], v110
	ds_read_b128 v[102:105], v110 offset:1024
	ds_read_b128 v[106:109], v110 offset:2048
	ds_read_b128 v[110:113], v110 offset:3072
	ds_read_b128 v[156:159], v174
	ds_read_b128 v[166:169], v174 offset:1024
	ds_read_b128 v[170:173], v174 offset:2048
	ds_read_b128 v[174:177], v174 offset:3072
	v_lshl_add_u64 v[218:219], s[0:1], 0, v[150:151]
	s_mov_b32 m0, s22
	s_nop 0
	global_load_lds_dwordx4 v[218:219], off
	v_lshl_add_u64 v[218:219], s[0:1], 0, v[148:149]
	s_mov_b32 m0, s23
	s_nop 0
	global_load_lds_dwordx4 v[218:219], off
	s_add_u32 s0, s0, 0x4000
	s_addc_u32 s1, s1, 0
	s_mov_b32 m0, s24
	v_lshl_add_u64 v[218:219], s[0:1], 0, v[150:151]
	ds_read_b128 v[178:181], v165 offset:32768
	ds_read_b128 v[182:185], v165 offset:33792
	ds_read_b128 v[186:189], v165 offset:34816
	ds_read_b128 v[190:193], v165 offset:35840
	ds_read_b128 v[194:197], v165 offset:36864
	ds_read_b128 v[198:201], v165 offset:37888
	ds_read_b128 v[202:205], v165 offset:38912
	ds_read_b128 v[206:209], v165 offset:39936
	global_load_lds_dwordx4 v[218:219], off
	v_lshl_add_u64 v[218:219], s[0:1], 0, v[148:149]
	s_mov_b32 m0, s25
	s_nop 0
	global_load_lds_dwordx4 v[218:219], off
	s_waitcnt vmcnt(8)
	s_waitcnt lgkmcnt(0)
	s_barrier
	s_setprio 1
	s_waitcnt lgkmcnt(0)
	v_mfma_f32_16x16x32_bf16 v[142:145], v[98:101], v[178:181], v[142:145]
	v_mfma_f32_16x16x32_bf16 v[138:141], v[106:109], v[178:181], v[138:141]
	v_mfma_f32_16x16x32_bf16 v[126:129], v[98:101], v[186:189], v[126:129]
	v_mfma_f32_16x16x32_bf16 v[122:125], v[106:109], v[186:189], v[122:125]
	v_mfma_f32_16x16x32_bf16 v[94:97], v[98:101], v[194:197], v[94:97]
	v_mfma_f32_16x16x32_bf16 v[90:93], v[106:109], v[194:197], v[90:93]
	v_mfma_f32_16x16x32_bf16 v[78:81], v[98:101], v[202:205], v[78:81]
	v_mfma_f32_16x16x32_bf16 v[74:77], v[106:109], v[202:205], v[74:77]
	v_mfma_f32_16x16x32_bf16 v[142:145], v[102:105], v[182:185], v[142:145]
	v_mfma_f32_16x16x32_bf16 v[138:141], v[110:113], v[182:185], v[138:141]
	v_mfma_f32_16x16x32_bf16 v[126:129], v[102:105], v[190:193], v[126:129]
	v_mfma_f32_16x16x32_bf16 v[122:125], v[110:113], v[190:193], v[122:125]
	v_mfma_f32_16x16x32_bf16 v[94:97], v[102:105], v[198:201], v[94:97]
	v_mfma_f32_16x16x32_bf16 v[90:93], v[110:113], v[198:201], v[90:93]
	v_mfma_f32_16x16x32_bf16 v[78:81], v[102:105], v[206:209], v[78:81]
	v_mfma_f32_16x16x32_bf16 v[74:77], v[110:113], v[206:209], v[74:77]
	s_setprio 0
	s_setprio 1
	v_mfma_f32_16x16x32_bf16 v[134:137], v[156:159], v[178:181], v[134:137]
	v_mfma_f32_16x16x32_bf16 v[130:133], v[170:173], v[178:181], v[130:133]
	v_mfma_f32_16x16x32_bf16 v[118:121], v[156:159], v[186:189], v[118:121]
	v_mfma_f32_16x16x32_bf16 v[114:117], v[170:173], v[186:189], v[114:117]
	v_mfma_f32_16x16x32_bf16 v[86:89], v[156:159], v[194:197], v[86:89]
	v_mfma_f32_16x16x32_bf16 v[82:85], v[170:173], v[194:197], v[82:85]
	v_mfma_f32_16x16x32_bf16 v[70:73], v[156:159], v[202:205], v[70:73]
	v_mfma_f32_16x16x32_bf16 v[66:69], v[170:173], v[202:205], v[66:69]
	v_mfma_f32_16x16x32_bf16 v[134:137], v[166:169], v[182:185], v[134:137]
	v_mfma_f32_16x16x32_bf16 v[130:133], v[174:177], v[182:185], v[130:133]
	v_mfma_f32_16x16x32_bf16 v[118:121], v[166:169], v[190:193], v[118:121]
	v_mfma_f32_16x16x32_bf16 v[114:117], v[174:177], v[190:193], v[114:117]
	v_mfma_f32_16x16x32_bf16 v[86:89], v[166:169], v[198:201], v[86:89]
	v_mfma_f32_16x16x32_bf16 v[82:85], v[174:177], v[198:201], v[82:85]
	v_mfma_f32_16x16x32_bf16 v[70:73], v[166:169], v[206:209], v[70:73]
	v_mfma_f32_16x16x32_bf16 v[66:69], v[174:177], v[206:209], v[66:69]
	s_setprio 0
	s_barrier
	s_add_i32 s0, s39, s20
	v_lshl_add_u64 v[160:161], v[160:161], 0, s[48:49]
	s_mov_b32 m0, s0
	ds_read_b128 v[178:181], v165 offset:49152
	ds_read_b128 v[182:185], v165 offset:50176
	ds_read_b128 v[186:189], v165 offset:51200
	ds_read_b128 v[190:193], v165 offset:52224
	ds_read_b128 v[194:197], v165 offset:53248
	ds_read_b128 v[198:201], v165 offset:54272
	ds_read_b128 v[202:205], v165 offset:55296
	ds_read_b128 v[206:209], v165 offset:56320
	global_load_lds_dwordx4 v[160:161], off
	s_add_i32 m0, s0, 0x2000
	s_add_u32 s0, s18, 0x160080
	v_lshl_add_u64 v[160:161], v[216:217], 0, s[48:49]
	s_addc_u32 s1, s19, 0
	s_add_i32 s18, s40, s20
	global_load_lds_dwordx4 v[160:161], off
	v_lshl_add_u64 v[160:161], s[0:1], 0, v[210:211]
	s_mov_b32 m0, s18
	s_nop 0
	global_load_lds_dwordx4 v[160:161], off
	v_lshl_add_u64 v[160:161], s[0:1], 0, v[146:147]
	s_add_i32 m0, s18, 0x2000
	s_nop 0
	global_load_lds_dwordx4 v[160:161], off
	v_lshl_add_u64 v[160:161], s[16:17], 0, v[150:151]
	s_mov_b32 m0, s26
	s_nop 0
	global_load_lds_dwordx4 v[160:161], off
	v_lshl_add_u64 v[160:161], s[16:17], 0, v[148:149]
	s_mov_b32 m0, s27
	s_nop 0
	global_load_lds_dwordx4 v[160:161], off
	s_waitcnt vmcnt(6)
	s_waitcnt lgkmcnt(0)
	s_barrier
	s_setprio 1
	s_waitcnt lgkmcnt(0)
	v_mfma_f32_16x16x32_bf16 v[62:65], v[98:101], v[178:181], v[62:65]
	v_mfma_f32_16x16x32_bf16 v[58:61], v[106:109], v[178:181], v[58:61]
	v_mfma_f32_16x16x32_bf16 v[50:53], v[98:101], v[186:189], v[50:53]
	v_mfma_f32_16x16x32_bf16 v[42:45], v[106:109], v[186:189], v[42:45]
	v_mfma_f32_16x16x32_bf16 v[34:37], v[98:101], v[194:197], v[34:37]
	v_mfma_f32_16x16x32_bf16 v[26:29], v[106:109], v[194:197], v[26:29]
	v_mfma_f32_16x16x32_bf16 v[18:21], v[98:101], v[202:205], v[18:21]
	v_mfma_f32_16x16x32_bf16 v[10:13], v[106:109], v[202:205], v[10:13]
	v_mfma_f32_16x16x32_bf16 v[62:65], v[102:105], v[182:185], v[62:65]
	v_mfma_f32_16x16x32_bf16 v[58:61], v[110:113], v[182:185], v[58:61]
	v_mfma_f32_16x16x32_bf16 v[50:53], v[102:105], v[190:193], v[50:53]
	v_mfma_f32_16x16x32_bf16 v[42:45], v[110:113], v[190:193], v[42:45]
	v_mfma_f32_16x16x32_bf16 v[34:37], v[102:105], v[198:201], v[34:37]
	v_mfma_f32_16x16x32_bf16 v[26:29], v[110:113], v[198:201], v[26:29]
	v_mfma_f32_16x16x32_bf16 v[18:21], v[102:105], v[206:209], v[18:21]
	v_mfma_f32_16x16x32_bf16 v[10:13], v[110:113], v[206:209], v[10:13]
	s_setprio 0
	s_setprio 1
	v_mfma_f32_16x16x32_bf16 v[54:57], v[156:159], v[178:181], v[54:57]
	v_mfma_f32_16x16x32_bf16 v[46:49], v[170:173], v[178:181], v[46:49]
	v_mfma_f32_16x16x32_bf16 v[38:41], v[156:159], v[186:189], v[38:41]
	v_mfma_f32_16x16x32_bf16 v[30:33], v[170:173], v[186:189], v[30:33]
	v_mfma_f32_16x16x32_bf16 v[22:25], v[156:159], v[194:197], v[22:25]
	v_mfma_f32_16x16x32_bf16 v[14:17], v[170:173], v[194:197], v[14:17]
	v_mfma_f32_16x16x32_bf16 v[6:9], v[156:159], v[202:205], v[6:9]
	v_mfma_f32_16x16x32_bf16 v[2:5], v[170:173], v[202:205], v[2:5]
	v_mfma_f32_16x16x32_bf16 v[54:57], v[166:169], v[182:185], v[54:57]
	v_mfma_f32_16x16x32_bf16 v[46:49], v[174:177], v[182:185], v[46:49]
	v_mfma_f32_16x16x32_bf16 v[38:41], v[166:169], v[190:193], v[38:41]
	v_mfma_f32_16x16x32_bf16 v[30:33], v[174:177], v[190:193], v[30:33]
	v_mfma_f32_16x16x32_bf16 v[22:25], v[166:169], v[198:201], v[22:25]
	v_mfma_f32_16x16x32_bf16 v[14:17], v[174:177], v[198:201], v[14:17]
	v_mfma_f32_16x16x32_bf16 v[6:9], v[166:169], v[206:209], v[6:9]
	v_mfma_f32_16x16x32_bf16 v[2:5], v[174:177], v[206:209], v[2:5]
	s_setprio 0
	s_barrier
	s_add_i32 s38, s38, 2
	s_add_u32 s36, s36, 0x100
	s_addc_u32 s37, s37, 0
	s_add_u32 s14, s14, 0x10000
	s_addc_u32 s15, s15, 0
	s_cmpk_gt_u32 s38, 0x55
	s_cbranch_scc0 .LBB0_1015
	s_and_b64 vcc, exec, s[10:11]
	s_cbranch_vccz .LBB0_1018
	s_barrier
